# attention main loop: first 4 PV MFMAs of each step hoisted into the DMA-issue/row-max window; EpiRes per-row counted waits; on top of EpiPle v2 + kl3b
# speedup vs baseline: 1.0108x; 1.0009x over previous
.LBB0_369:
	s_lshl_b32 s20, s20, 1
	v_add_u32_e32 v187, s20, v224
	ds_read_b128 v[96:99], v222
	ds_read_b128 v[228:231], v222 offset:1024
	ds_read_b128 v[232:235], v222 offset:2048
	ds_read_b128 v[248:251], v222 offset:3072
	ds_read_b64_tr_b16 v[176:177], v187 offset:24576
	ds_read_b64_tr_b16 v[178:179], v187 offset:25088
	s_waitcnt lgkmcnt(5)
	v_mfma_f32_32x32x16_bf16 v[112:127], v[168:171], v[96:99], 0
	v_add_f32_e32 v100, v80, v81
	v_add_f32_e32 v100, v82, v100
	v_add_f32_e32 v100, v83, v100
	v_add_f32_e32 v100, v84, v100
	v_add_f32_e32 v100, v85, v100
	v_cvt_pk_bf16_f32 v140, v80, v81
	v_cvt_pk_bf16_f32 v141, v82, v83
	ds_read_b64_tr_b16 v[168:169], v187 offset:28672
	ds_read_b64_tr_b16 v[170:171], v187 offset:29184
	v_add_f32_e32 v80, v86, v100
	v_mfma_f32_32x32x16_bf16 v[96:111], v[160:163], v[96:99], 0
	v_add_f32_e32 v80, v87, v80
	v_add_f32_e32 v80, v88, v80
	v_add_f32_e32 v80, v89, v80
	v_cvt_pk_bf16_f32 v142, v84, v85
	v_cvt_pk_bf16_f32 v143, v86, v87
	ds_read_b64_tr_b16 v[84:85], v187 offset:32768
	ds_read_b64_tr_b16 v[86:87], v187 offset:33280
	s_waitcnt lgkmcnt(8)
	v_mfma_f32_32x32x16_bf16 v[112:127], v[172:175], v[228:231], v[112:127]
	v_add_f32_e32 v80, v90, v80
	v_add_f32_e32 v80, v91, v80
	v_add_f32_e32 v80, v92, v80
	v_add_f32_e32 v128, v93, v80
	v_cvt_pk_bf16_f32 v136, v88, v89
	v_cvt_pk_bf16_f32 v137, v90, v91
	ds_read_b64_tr_b16 v[80:81], v187 offset:36864
	ds_read_b64_tr_b16 v[82:83], v187 offset:37376
	v_mfma_f32_32x32x16_bf16 v[96:111], v[156:159], v[228:231], v[96:111]
	v_add_f32_e32 v88, v94, v128
	v_add_f32_e32 v88, v95, v88
	v_add_f32_e32 v88, v64, v88
	v_add_f32_e32 v88, v65, v88
	v_cvt_pk_bf16_f32 v138, v92, v93
	v_cvt_pk_bf16_f32 v139, v94, v95
	ds_read_b64_tr_b16 v[92:93], v187 offset:25600
	ds_read_b64_tr_b16 v[94:95], v187 offset:26112
	s_waitcnt lgkmcnt(11)
	v_mfma_f32_32x32x16_bf16 v[112:127], v[164:167], v[232:235], v[112:127]
	v_add_f32_e32 v88, v66, v88
	v_add_f32_e32 v88, v67, v88
	v_add_f32_e32 v88, v68, v88
	v_add_f32_e32 v128, v69, v88
	v_cvt_pk_bf16_f32 v132, v64, v65
	v_cvt_pk_bf16_f32 v133, v66, v67
	ds_read_b64_tr_b16 v[88:89], v187 offset:29696
	ds_read_b64_tr_b16 v[90:91], v187 offset:30208
	v_mfma_f32_32x32x16_bf16 v[96:111], v[148:151], v[232:235], v[96:111]
	v_add_f32_e32 v64, v70, v128
	v_add_f32_e32 v64, v71, v64
	v_add_f32_e32 v64, v72, v64
	v_add_f32_e32 v64, v73, v64
	v_cvt_pk_bf16_f32 v134, v68, v69
	v_cvt_pk_bf16_f32 v135, v70, v71
	ds_read_b64_tr_b16 v[68:69], v187 offset:33792
	ds_read_b64_tr_b16 v[70:71], v187 offset:34304
	s_waitcnt lgkmcnt(14)
	v_mfma_f32_32x32x16_bf16 v[112:127], v[152:155], v[248:251], v[112:127]
	v_add_f32_e32 v64, v74, v64
	v_add_f32_e32 v64, v75, v64
	v_add_f32_e32 v64, v76, v64
	v_add_f32_e32 v148, v77, v64
	v_cvt_pk_bf16_f32 v128, v72, v73
	v_cvt_pk_bf16_f32 v129, v74, v75
	ds_read_b64_tr_b16 v[64:65], v187 offset:37888
	ds_read_b64_tr_b16 v[66:67], v187 offset:38400
	v_mfma_f32_32x32x16_bf16 v[96:111], v[144:147], v[248:251], v[96:111]
	v_add_f32_e32 v72, v78, v148
	v_add_f32_e32 v72, v79, v72
	v_add_f32_e32 v74, 0, v72
	v_cvt_pk_bf16_f32 v130, v76, v77
	v_cvt_pk_bf16_f32 v131, v78, v79
	s_waitcnt lgkmcnt(14)
	v_mfma_f32_32x32x16_bf16 v[32:47], v[140:143], v[176:179], v[32:47]
	v_lshl_add_u64 v[72:73], v[184:185], 0, s[90:91]
	s_add_i32 s20, s29, s42
	s_mov_b32 s21, m0
	s_mov_b32 m0, s20
	s_nop 0
	global_load_lds_dwordx4 v[72:73], off
	s_mov_b32 m0, s21
	s_waitcnt lgkmcnt(12)
	v_mfma_f32_32x32x16_bf16 v[48:63], v[140:143], v[168:171], v[48:63]
	s_movk_i32 s20, 0xc000
	s_mov_b32 s21, -1
	v_lshl_add_u64 v[72:73], v[182:183], 0, s[20:21]
	s_lshl_b32 s20, s28, 1
	s_add_i32 s20, s20, s43
	s_mov_b32 s21, m0
	s_mov_b32 m0, s20
	s_nop 0
	global_load_lds_dwordx4 v[72:73], off
	s_mov_b32 m0, s21
	s_waitcnt lgkmcnt(10)
	v_mfma_f32_32x32x16_bf16 v[16:31], v[140:143], v[84:87], v[16:31]
	v_lshl_add_u64 v[72:73], v[182:183], 0, s[90:91]
	s_addk_i32 s20, 0x2000
	s_mov_b32 s21, m0
	s_mov_b32 m0, s20
	s_nop 0
	global_load_lds_dwordx4 v[72:73], off
	s_mov_b32 m0, s21
	s_waitcnt lgkmcnt(8)
	v_mfma_f32_32x32x16_bf16 v[0:15], v[140:143], v[80:83], v[0:15]
	v_max_f32_e32 v72, v113, v113
	v_max_f32_e32 v73, v112, v112
	v_max_f32_e32 v72, v73, v72
	v_max3_f32 v73, v114, v115, v97
	v_max3_f32 v72, v72, v96, v98
	v_max3_f32 v72, v72, v99, v116
	v_max3_f32 v73, v73, v118, v119
	v_max3_f32 v72, v72, v117, v100
	v_max3_f32 v73, v73, v102, v103
	v_max3_f32 v72, v72, v101, v120
	v_max3_f32 v73, v73, v122, v123
	v_max3_f32 v72, v72, v121, v104
	v_max3_f32 v73, v73, v106, v107
	v_max3_f32 v72, v72, v105, v124
	v_max3_f32 v73, v73, v126, v127
	v_max3_f32 v72, v72, v125, v108
	v_max3_f32 v73, v73, v110, v111
	v_max3_f32 v72, v72, v109, v73
	v_mov_b32_e32 v73, v72
	s_nop 1
	v_permlane32_swap_b32_e32 v72, v73
	v_max_f32_e32 v73, v73, v73
	v_max_f32_e32 v72, v72, v72
	v_max_f32_e32 v72, v72, v73
	v_sub_f32_e32 v72, v72, v220
	v_cmp_lt_f32_e32 vcc, s92, v72
	s_cmp_lg_u64 vcc, 0
	v_add_f32_e32 v190, v226, v74
	s_cselect_b64 s[20:21], -1, 0
	s_cbranch_vccnz .LBB0_377
.LBB0_370:
	v_sub_f32_e32 v72, v112, v220
	v_exp_f32_e32 v112, v72
	v_sub_f32_e32 v72, v113, v220
	v_exp_f32_e32 v113, v72
	ds_read_b64_tr_b16 v[72:73], v187 offset:26624
	ds_read_b64_tr_b16 v[74:75], v187 offset:27136
	v_sub_f32_e32 v76, v114, v220
	v_exp_f32_e32 v114, v76
	v_sub_f32_e32 v76, v115, v220
	v_exp_f32_e32 v115, v76
	ds_read_b64_tr_b16 v[76:77], v187 offset:30720
	ds_read_b64_tr_b16 v[78:79], v187 offset:31232
	v_sub_f32_e32 v84, v116, v220
	v_exp_f32_e32 v116, v84
	v_sub_f32_e32 v84, v117, v220
	v_exp_f32_e32 v117, v84
	ds_read_b64_tr_b16 v[84:85], v187 offset:34816
	ds_read_b64_tr_b16 v[86:87], v187 offset:35328
	v_sub_f32_e32 v80, v118, v220
	v_exp_f32_e32 v118, v80
	v_sub_f32_e32 v80, v119, v220
	v_exp_f32_e32 v119, v80
	ds_read_b64_tr_b16 v[80:81], v187 offset:38912
	ds_read_b64_tr_b16 v[82:83], v187 offset:39424
	s_waitcnt lgkmcnt(14)
	v_mfma_f32_32x32x16_bf16 v[32:47], v[136:139], v[92:95], v[32:47]
	v_sub_f32_e32 v92, v120, v220
	v_exp_f32_e32 v120, v92
	v_sub_f32_e32 v92, v121, v220
	v_exp_f32_e32 v121, v92
	ds_read_b64_tr_b16 v[92:93], v187 offset:27648
	ds_read_b64_tr_b16 v[94:95], v187 offset:28160
	s_waitcnt lgkmcnt(14)
	v_mfma_f32_32x32x16_bf16 v[48:63], v[136:139], v[88:91], v[48:63]
	v_sub_f32_e32 v88, v122, v220
	v_exp_f32_e32 v122, v88
	v_sub_f32_e32 v88, v123, v220
	v_exp_f32_e32 v123, v88
	ds_read_b64_tr_b16 v[88:89], v187 offset:31744
	ds_read_b64_tr_b16 v[90:91], v187 offset:32256
	s_waitcnt lgkmcnt(14)
	v_mfma_f32_32x32x16_bf16 v[16:31], v[136:139], v[68:71], v[16:31]
	v_sub_f32_e32 v68, v124, v220
	v_exp_f32_e32 v124, v68
	v_sub_f32_e32 v68, v125, v220
	v_exp_f32_e32 v125, v68
	ds_read_b64_tr_b16 v[168:169], v187 offset:35840
	ds_read_b64_tr_b16 v[170:171], v187 offset:36352
	s_waitcnt lgkmcnt(14)
	v_mfma_f32_32x32x16_bf16 v[0:15], v[136:139], v[64:67], v[0:15]
	v_sub_f32_e32 v64, v126, v220
	v_exp_f32_e32 v126, v64
	v_sub_f32_e32 v64, v127, v220
	v_exp_f32_e32 v127, v64
	ds_read_b64_tr_b16 v[172:173], v187 offset:39936
	ds_read_b64_tr_b16 v[174:175], v187 offset:40448
	v_add_u32_e32 v136, s28, v223
	ds_read_b128 v[68:71], v136
	ds_read_b128 v[64:67], v136 offset:512
	s_waitcnt lgkmcnt(14)
	v_mfma_f32_32x32x16_bf16 v[32:47], v[132:135], v[72:75], v[32:47]
	v_sub_f32_e32 v72, v96, v220
	v_exp_f32_e32 v96, v72
	v_sub_f32_e32 v72, v97, v220
	v_exp_f32_e32 v97, v72
	v_mfma_f32_32x32x16_bf16 v[48:63], v[132:135], v[76:79], v[48:63]
	v_sub_f32_e32 v72, v98, v220
	v_exp_f32_e32 v98, v72
	v_sub_f32_e32 v72, v99, v220
	v_exp_f32_e32 v99, v72
	ds_read_b128 v[164:167], v136 offset:2048
	ds_read_b128 v[152:155], v136 offset:2560
	s_waitcnt lgkmcnt(14)
	v_mfma_f32_32x32x16_bf16 v[16:31], v[132:135], v[84:87], v[16:31]
	v_sub_f32_e32 v72, v100, v220
	v_exp_f32_e32 v100, v72
	v_sub_f32_e32 v72, v101, v220
	v_exp_f32_e32 v101, v72
	s_waitcnt lgkmcnt(12)
	v_mfma_f32_32x32x16_bf16 v[0:15], v[132:135], v[80:83], v[0:15]
	v_sub_f32_e32 v72, v102, v220
	v_exp_f32_e32 v102, v72
	v_sub_f32_e32 v72, v103, v220
	v_exp_f32_e32 v103, v72
	ds_read_b128 v[160:163], v136 offset:4096
	ds_read_b128 v[148:151], v136 offset:4608
	s_waitcnt lgkmcnt(12)
	v_mfma_f32_32x32x16_bf16 v[32:47], v[128:131], v[92:95], v[32:47]
	v_sub_f32_e32 v72, v104, v220
	v_exp_f32_e32 v104, v72
	v_sub_f32_e32 v72, v105, v220
	v_exp_f32_e32 v105, v72
	s_waitcnt lgkmcnt(10)
	v_mfma_f32_32x32x16_bf16 v[48:63], v[128:131], v[88:91], v[48:63]
	v_sub_f32_e32 v72, v106, v220
	v_exp_f32_e32 v106, v72
	v_sub_f32_e32 v72, v107, v220
	v_exp_f32_e32 v107, v72
	ds_read_b128 v[156:159], v136 offset:6144
	ds_read_b128 v[144:147], v136 offset:6656
	s_waitcnt lgkmcnt(10)
	v_mfma_f32_32x32x16_bf16 v[16:31], v[128:131], v[168:171], v[16:31]
	v_sub_f32_e32 v72, v108, v220
	v_exp_f32_e32 v108, v72
	v_sub_f32_e32 v72, v109, v220
	v_exp_f32_e32 v109, v72
	s_waitcnt lgkmcnt(8)
	v_mfma_f32_32x32x16_bf16 v[0:15], v[128:131], v[172:175], v[0:15]
	v_sub_f32_e32 v72, v110, v220
	v_exp_f32_e32 v110, v72
	v_sub_f32_e32 v72, v111, v220
	v_exp_f32_e32 v111, v72
	s_waitcnt vmcnt(3) lgkmcnt(0)
	s_barrier
	s_andn2_b64 vcc, exec, s[20:21]
	v_add_u32_e32 v187, s34, v225
	s_cbranch_vccnz .LBB0_372
	s_waitcnt lgkmcnt(0)
	ds_read_b128 v[72:75], v187 offset:96
	ds_read_b128 v[76:79], v187 offset:64
	ds_read_b128 v[80:83], v187 offset:32
	ds_read_b128 v[84:87], v187
	s_waitcnt lgkmcnt(3)
	v_pk_mul_f32 v[44:45], v[44:45], v[72:73]
	s_waitcnt lgkmcnt(2)
	v_pk_mul_f32 v[40:41], v[40:41], v[76:77]
	s_waitcnt lgkmcnt(1)
	v_pk_mul_f32 v[36:37], v[36:37], v[80:81]
	v_pk_mul_f32 v[46:47], v[46:47], v[74:75]
	v_pk_mul_f32 v[42:43], v[42:43], v[78:79]
	v_pk_mul_f32 v[38:39], v[38:39], v[82:83]
	s_waitcnt lgkmcnt(0)
	v_pk_mul_f32 v[34:35], v[34:35], v[86:87]
	v_pk_mul_f32 v[32:33], v[32:33], v[84:85]
	v_pk_mul_f32 v[60:61], v[60:61], v[72:73]
	v_pk_mul_f32 v[56:57], v[56:57], v[76:77]
	v_pk_mul_f32 v[52:53], v[52:53], v[80:81]
	v_pk_mul_f32 v[62:63], v[62:63], v[74:75]
	v_pk_mul_f32 v[58:59], v[58:59], v[78:79]
	v_pk_mul_f32 v[54:55], v[54:55], v[82:83]
	v_pk_mul_f32 v[50:51], v[50:51], v[86:87]
	v_pk_mul_f32 v[48:49], v[48:49], v[84:85]
	v_pk_mul_f32 v[28:29], v[28:29], v[72:73]
	v_pk_mul_f32 v[24:25], v[24:25], v[76:77]
	v_pk_mul_f32 v[20:21], v[20:21], v[80:81]
	v_pk_mul_f32 v[30:31], v[30:31], v[74:75]
	v_pk_mul_f32 v[26:27], v[26:27], v[78:79]
	v_pk_mul_f32 v[22:23], v[22:23], v[82:83]
	v_pk_mul_f32 v[18:19], v[18:19], v[86:87]
	v_pk_mul_f32 v[16:17], v[16:17], v[84:85]
	v_pk_mul_f32 v[12:13], v[12:13], v[72:73]
	v_pk_mul_f32 v[8:9], v[8:9], v[76:77]
	v_pk_mul_f32 v[4:5], v[4:5], v[80:81]
	v_pk_mul_f32 v[14:15], v[14:15], v[74:75]
	v_pk_mul_f32 v[10:11], v[10:11], v[78:79]
	v_pk_mul_f32 v[6:7], v[6:7], v[82:83]
	v_pk_mul_f32 v[2:3], v[2:3], v[86:87]
	v_pk_mul_f32 v[0:1], v[0:1], v[84:85]
.LBB0_372:
	s_add_i32 s20, s28, 0x2000
	s_cmpk_lg_i32 s28, 0x4000
	s_cselect_b32 s97, s20, 0
	s_lshl_b32 s20, s29, 1
	v_add_u32_e32 v191, s20, v224
	ds_read_b128 v[72:75], v222
	ds_read_b128 v[226:229], v222 offset:1024
	ds_read_b128 v[230:233], v222 offset:2048
	ds_read_b128 v[234:237], v222 offset:3072
	ds_read_b64_tr_b16 v[176:177], v191 offset:24576
	ds_read_b64_tr_b16 v[178:179], v191 offset:25088
	s_waitcnt lgkmcnt(5)
	v_mfma_f32_32x32x16_bf16 v[80:95], v[68:71], v[72:75], 0
	v_add_f32_e32 v76, v112, v113
	v_add_f32_e32 v76, v114, v76
	v_add_f32_e32 v76, v115, v76
	v_add_f32_e32 v76, v116, v76
	v_add_f32_e32 v76, v117, v76
	v_cvt_pk_bf16_f32 v140, v112, v113
	v_cvt_pk_bf16_f32 v141, v114, v115
	ds_read_b64_tr_b16 v[172:173], v191 offset:28672
	ds_read_b64_tr_b16 v[174:175], v191 offset:29184
	v_add_f32_e32 v68, v118, v76
	v_add_f32_e32 v68, v119, v68
	v_add_f32_e32 v68, v120, v68
	v_add_f32_e32 v112, v121, v68
	v_mfma_f32_32x32x16_bf16 v[64:79], v[64:67], v[72:75], 0
	v_cvt_pk_bf16_f32 v142, v116, v117
	v_cvt_pk_bf16_f32 v143, v118, v119
	ds_read_b64_tr_b16 v[168:169], v191 offset:32768
	ds_read_b64_tr_b16 v[170:171], v191 offset:33280
	s_waitcnt lgkmcnt(8)
	v_mfma_f32_32x32x16_bf16 v[80:95], v[164:167], v[226:229], v[80:95]
	v_add_f32_e32 v112, v122, v112
	v_add_f32_e32 v112, v123, v112
	v_add_f32_e32 v112, v124, v112
	v_add_f32_e32 v112, v125, v112
	v_cvt_pk_bf16_f32 v136, v120, v121
	v_cvt_pk_bf16_f32 v137, v122, v123
	ds_read_b64_tr_b16 v[120:121], v191 offset:36864
	ds_read_b64_tr_b16 v[122:123], v191 offset:37376
	v_mfma_f32_32x32x16_bf16 v[64:79], v[152:155], v[226:229], v[64:79]
	v_add_f32_e32 v112, v126, v112
	v_add_f32_e32 v112, v127, v112
	v_add_f32_e32 v112, v96, v112
	v_add_f32_e32 v112, v97, v112
	v_cvt_pk_bf16_f32 v138, v124, v125
	v_cvt_pk_bf16_f32 v139, v126, v127
	ds_read_b64_tr_b16 v[116:117], v191 offset:25600
	ds_read_b64_tr_b16 v[118:119], v191 offset:26112
	s_waitcnt lgkmcnt(11)
	v_mfma_f32_32x32x16_bf16 v[80:95], v[160:163], v[230:233], v[80:95]
	v_add_f32_e32 v112, v98, v112
	v_add_f32_e32 v112, v99, v112
	v_add_f32_e32 v112, v100, v112
	v_add_f32_e32 v124, v101, v112
	v_cvt_pk_bf16_f32 v132, v96, v97
	v_cvt_pk_bf16_f32 v133, v98, v99
	ds_read_b64_tr_b16 v[112:113], v191 offset:29696
	ds_read_b64_tr_b16 v[114:115], v191 offset:30208
	v_mfma_f32_32x32x16_bf16 v[64:79], v[148:151], v[230:233], v[64:79]
	v_add_f32_e32 v96, v102, v124
	v_add_f32_e32 v96, v103, v96
	v_add_f32_e32 v96, v104, v96
	v_add_f32_e32 v96, v105, v96
	v_cvt_pk_bf16_f32 v134, v100, v101
	v_cvt_pk_bf16_f32 v135, v102, v103
	ds_read_b64_tr_b16 v[100:101], v191 offset:33792
	ds_read_b64_tr_b16 v[102:103], v191 offset:34304
	s_waitcnt lgkmcnt(14)
	v_mfma_f32_32x32x16_bf16 v[80:95], v[156:159], v[234:237], v[80:95]
	v_add_f32_e32 v96, v106, v96
	v_add_f32_e32 v96, v107, v96
	v_add_f32_e32 v96, v108, v96
	v_add_f32_e32 v124, v109, v96
	v_cvt_pk_bf16_f32 v128, v104, v105
	v_cvt_pk_bf16_f32 v129, v106, v107
	ds_read_b64_tr_b16 v[96:97], v191 offset:37888
	ds_read_b64_tr_b16 v[98:99], v191 offset:38400
	v_mfma_f32_32x32x16_bf16 v[64:79], v[144:147], v[234:237], v[64:79]
	v_add_f32_e32 v104, v110, v124
	v_add_f32_e32 v104, v111, v104
	v_add_f32_e32 v106, 0, v104
	v_cvt_pk_bf16_f32 v130, v108, v109
	v_cvt_pk_bf16_f32 v131, v110, v111
	s_waitcnt lgkmcnt(14)
	v_mfma_f32_32x32x16_bf16 v[32:47], v[140:143], v[176:179], v[32:47]
	s_add_i32 s20, s28, s42
	s_mov_b32 s21, m0
	s_mov_b32 m0, s20
	s_nop 0
	global_load_lds_dwordx4 v[184:185], off
	s_mov_b32 m0, s21
	s_waitcnt lgkmcnt(12)
	v_mfma_f32_32x32x16_bf16 v[48:63], v[140:143], v[172:175], v[48:63]
	s_lshl_b32 s20, s97, 1
	s_add_i32 s20, s20, s43
	s_mov_b32 s21, m0
	s_mov_b32 m0, s20
	s_nop 0
	global_load_lds_dwordx4 v[182:183], off
	s_mov_b32 m0, s21
	s_waitcnt lgkmcnt(10)
	v_mfma_f32_32x32x16_bf16 v[16:31], v[140:143], v[168:171], v[16:31]
	v_lshl_add_u64 v[104:105], v[182:183], 0, s[84:85]
	s_addk_i32 s20, 0x2000
	s_mov_b32 s21, m0
	s_mov_b32 m0, s20
	s_nop 0
	global_load_lds_dwordx4 v[104:105], off
	s_mov_b32 m0, s21
	s_waitcnt lgkmcnt(8)
	v_mfma_f32_32x32x16_bf16 v[0:15], v[140:143], v[120:123], v[0:15]
	v_max_f32_e32 v104, v81, v81
	v_max_f32_e32 v105, v80, v80
	v_max_f32_e32 v104, v105, v104
	v_max3_f32 v105, v82, v83, v65
	v_max3_f32 v104, v104, v64, v66
	v_max3_f32 v104, v104, v67, v84
	v_max3_f32 v105, v105, v86, v87
	v_max3_f32 v104, v104, v85, v68
	v_max3_f32 v105, v105, v70, v71
	v_max3_f32 v104, v104, v69, v88
	v_max3_f32 v105, v105, v90, v91
	v_max3_f32 v104, v104, v89, v72
	v_max3_f32 v105, v105, v74, v75
	v_max3_f32 v104, v104, v73, v92
	v_max3_f32 v105, v105, v94, v95
	v_max3_f32 v104, v104, v93, v76
	v_max3_f32 v105, v105, v78, v79
	v_max3_f32 v104, v104, v77, v105
	v_mov_b32_e32 v105, v104
	s_nop 1
	v_permlane32_swap_b32_e32 v104, v105
	v_max_f32_e32 v105, v105, v105
	v_max_f32_e32 v104, v104, v104
	v_max_f32_e32 v104, v104, v105
	v_sub_f32_e32 v104, v104, v220
	v_cmp_lt_f32_e32 vcc, s92, v104
	s_cmp_lg_u64 vcc, 0
	v_add_f32_e32 v226, v190, v106
	s_cselect_b64 s[20:21], -1, 0
	s_cbranch_vccnz .LBB0_380
.LBB0_373:
	v_sub_f32_e32 v80, v80, v220
	v_sub_f32_e32 v81, v81, v220
	v_exp_f32_e32 v80, v80
	v_exp_f32_e32 v81, v81
	ds_read_b64_tr_b16 v[104:105], v191 offset:26624
	ds_read_b64_tr_b16 v[106:107], v191 offset:27136
	v_sub_f32_e32 v82, v82, v220
	v_sub_f32_e32 v83, v83, v220
	v_exp_f32_e32 v82, v82
	v_exp_f32_e32 v83, v83
	ds_read_b64_tr_b16 v[108:109], v191 offset:30720
	ds_read_b64_tr_b16 v[110:111], v191 offset:31232
	v_sub_f32_e32 v84, v84, v220
	v_sub_f32_e32 v85, v85, v220
	v_exp_f32_e32 v84, v84
	v_exp_f32_e32 v85, v85
	ds_read_b64_tr_b16 v[124:125], v191 offset:34816
	ds_read_b64_tr_b16 v[126:127], v191 offset:35328
	v_sub_f32_e32 v86, v86, v220
	v_sub_f32_e32 v87, v87, v220
	v_exp_f32_e32 v86, v86
	v_exp_f32_e32 v87, v87
	ds_read_b64_tr_b16 v[120:121], v191 offset:38912
	ds_read_b64_tr_b16 v[122:123], v191 offset:39424
	s_waitcnt lgkmcnt(14)
	v_mfma_f32_32x32x16_bf16 v[32:47], v[136:139], v[116:119], v[32:47]
	v_sub_f32_e32 v88, v88, v220
	v_sub_f32_e32 v89, v89, v220
	v_exp_f32_e32 v88, v88
	v_exp_f32_e32 v89, v89
	ds_read_b64_tr_b16 v[116:117], v191 offset:27648
	ds_read_b64_tr_b16 v[118:119], v191 offset:28160
	s_waitcnt lgkmcnt(14)
	v_mfma_f32_32x32x16_bf16 v[48:63], v[136:139], v[112:115], v[48:63]
	v_sub_f32_e32 v90, v90, v220
	v_sub_f32_e32 v91, v91, v220
	v_exp_f32_e32 v90, v90
	v_exp_f32_e32 v91, v91
	ds_read_b64_tr_b16 v[112:113], v191 offset:31744
	ds_read_b64_tr_b16 v[114:115], v191 offset:32256
	s_waitcnt lgkmcnt(14)
	v_mfma_f32_32x32x16_bf16 v[16:31], v[136:139], v[100:103], v[16:31]
	v_sub_f32_e32 v92, v92, v220
	v_sub_f32_e32 v93, v93, v220
	v_exp_f32_e32 v92, v92
	v_exp_f32_e32 v93, v93
	ds_read_b64_tr_b16 v[100:101], v191 offset:35840
	ds_read_b64_tr_b16 v[102:103], v191 offset:36352
	s_waitcnt lgkmcnt(14)
	v_mfma_f32_32x32x16_bf16 v[0:15], v[136:139], v[96:99], v[0:15]
	v_sub_f32_e32 v94, v94, v220
	v_sub_f32_e32 v95, v95, v220
	v_exp_f32_e32 v94, v94
	v_exp_f32_e32 v95, v95
	ds_read_b64_tr_b16 v[96:97], v191 offset:39936
	ds_read_b64_tr_b16 v[98:99], v191 offset:40448
	v_add_u32_e32 v136, s97, v223
	ds_read_b128 v[168:171], v136
	ds_read_b128 v[160:163], v136 offset:512
	s_waitcnt lgkmcnt(14)
	v_mfma_f32_32x32x16_bf16 v[32:47], v[132:135], v[104:107], v[32:47]
	v_sub_f32_e32 v64, v64, v220
	v_sub_f32_e32 v65, v65, v220
	v_exp_f32_e32 v64, v64
	v_exp_f32_e32 v65, v65
	v_mfma_f32_32x32x16_bf16 v[48:63], v[132:135], v[108:111], v[48:63]
	v_sub_f32_e32 v66, v66, v220
	v_sub_f32_e32 v67, v67, v220
	v_exp_f32_e32 v66, v66
	v_exp_f32_e32 v67, v67
	ds_read_b128 v[172:175], v136 offset:2048
	ds_read_b128 v[156:159], v136 offset:2560
	s_waitcnt lgkmcnt(14)
	v_mfma_f32_32x32x16_bf16 v[16:31], v[132:135], v[124:127], v[16:31]
	v_sub_f32_e32 v68, v68, v220
	v_sub_f32_e32 v69, v69, v220
	v_exp_f32_e32 v68, v68
	v_exp_f32_e32 v69, v69
	s_waitcnt lgkmcnt(12)
	v_mfma_f32_32x32x16_bf16 v[0:15], v[132:135], v[120:123], v[0:15]
	v_sub_f32_e32 v70, v70, v220
	v_sub_f32_e32 v71, v71, v220
	v_exp_f32_e32 v70, v70
	v_exp_f32_e32 v71, v71
	ds_read_b128 v[164:167], v136 offset:4096
	ds_read_b128 v[148:151], v136 offset:4608
	s_waitcnt lgkmcnt(12)
	v_mfma_f32_32x32x16_bf16 v[32:47], v[128:131], v[116:119], v[32:47]
	v_sub_f32_e32 v72, v72, v220
	v_sub_f32_e32 v73, v73, v220
	v_exp_f32_e32 v72, v72
	v_exp_f32_e32 v73, v73
	s_waitcnt lgkmcnt(10)
	v_mfma_f32_32x32x16_bf16 v[48:63], v[128:131], v[112:115], v[48:63]
	v_sub_f32_e32 v74, v74, v220
	v_sub_f32_e32 v75, v75, v220
	v_exp_f32_e32 v74, v74
	v_exp_f32_e32 v75, v75
	ds_read_b128 v[152:155], v136 offset:6144
	ds_read_b128 v[144:147], v136 offset:6656
	s_waitcnt lgkmcnt(10)
	v_mfma_f32_32x32x16_bf16 v[16:31], v[128:131], v[100:103], v[16:31]
	v_sub_f32_e32 v76, v76, v220
	v_sub_f32_e32 v77, v77, v220
	v_exp_f32_e32 v76, v76
	v_exp_f32_e32 v77, v77
	s_waitcnt lgkmcnt(8)
	v_mfma_f32_32x32x16_bf16 v[0:15], v[128:131], v[96:99], v[0:15]
	v_sub_f32_e32 v78, v78, v220
	v_sub_f32_e32 v79, v79, v220
	v_exp_f32_e32 v78, v78
	v_exp_f32_e32 v79, v79
	s_waitcnt vmcnt(3) lgkmcnt(0)
	s_barrier
	s_andn2_b64 vcc, exec, s[20:21]
	s_cbranch_vccnz .LBB0_375
	s_waitcnt lgkmcnt(0)
	ds_read_b128 v[96:99], v187 offset:96
	ds_read_b128 v[100:103], v187 offset:64
	ds_read_b128 v[104:107], v187 offset:32
	ds_read_b128 v[108:111], v187
	s_waitcnt lgkmcnt(3)
	v_pk_mul_f32 v[44:45], v[44:45], v[96:97]
	s_waitcnt lgkmcnt(2)
	v_pk_mul_f32 v[40:41], v[40:41], v[100:101]
	s_waitcnt lgkmcnt(1)
	v_pk_mul_f32 v[36:37], v[36:37], v[104:105]
	v_pk_mul_f32 v[46:47], v[46:47], v[98:99]
	v_pk_mul_f32 v[42:43], v[42:43], v[102:103]
	v_pk_mul_f32 v[38:39], v[38:39], v[106:107]
	s_waitcnt lgkmcnt(0)
	v_pk_mul_f32 v[34:35], v[34:35], v[110:111]
	v_pk_mul_f32 v[32:33], v[32:33], v[108:109]
	v_pk_mul_f32 v[60:61], v[60:61], v[96:97]
	v_pk_mul_f32 v[56:57], v[56:57], v[100:101]
	v_pk_mul_f32 v[52:53], v[52:53], v[104:105]
	v_pk_mul_f32 v[62:63], v[62:63], v[98:99]
	v_pk_mul_f32 v[58:59], v[58:59], v[102:103]
	v_pk_mul_f32 v[54:55], v[54:55], v[106:107]
	v_pk_mul_f32 v[50:51], v[50:51], v[110:111]
	v_pk_mul_f32 v[48:49], v[48:49], v[108:109]
	v_pk_mul_f32 v[28:29], v[28:29], v[96:97]
	v_pk_mul_f32 v[24:25], v[24:25], v[100:101]
	v_pk_mul_f32 v[20:21], v[20:21], v[104:105]
	v_pk_mul_f32 v[30:31], v[30:31], v[98:99]
	v_pk_mul_f32 v[26:27], v[26:27], v[102:103]
	v_pk_mul_f32 v[22:23], v[22:23], v[106:107]
	v_pk_mul_f32 v[18:19], v[18:19], v[110:111]
	v_pk_mul_f32 v[16:17], v[16:17], v[108:109]
	v_pk_mul_f32 v[12:13], v[12:13], v[96:97]
	v_pk_mul_f32 v[8:9], v[8:9], v[100:101]
	v_pk_mul_f32 v[4:5], v[4:5], v[104:105]
	v_pk_mul_f32 v[14:15], v[14:15], v[98:99]
	v_pk_mul_f32 v[10:11], v[10:11], v[102:103]
	v_pk_mul_f32 v[6:7], v[6:7], v[106:107]
	v_pk_mul_f32 v[2:3], v[2:3], v[110:111]
	v_pk_mul_f32 v[0:1], v[0:1], v[108:109]

; __device__ __forceinline__ u32x4 pack8(const f32x4 v0, const f32x4 v1) { u32x4 w; w.x = cvt_pk_bf16(v0[0], v0[1]); w.y = cvt_pk_bf16(v0[2], v0[3]); w.z = cvt_pk_bf16(v1[0], v1[1]); w.w = cvt_pk_bf16(v1[2], v1[3]); return w; }
; __device__ __forceinline__ float sumsq8(const f32x4 a, const f32x4 b) { return ((a[0] * a[0] + a[1] * a[1]) + (a[2] * a[2] + a[3] * a[3])) + ((b[0] * b[0] + b[1] * b[1]) + (b[2] * b[2] + b[3] * b[3])); }
; __device__ __forceinline__ void unpack8(const u32x4 w, f32x4& a, f32x4& b) { a = (f32x4){bf_lo(w.x), bf_hi(w.x), bf_lo(w.y), bf_hi(w.y)}; b = (f32x4){bf_lo(w.z), bf_hi(w.z), bf_lo(w.w), bf_hi(w.w)}; }
;     __device__ __forceinline__ void operator()(const f32x4 (&acc)[2][2][4][2], const Unit& u, int wr, int wc, int fr, int fq) const {
;         const int row0 = u.pm * BM + wr * 64 + fr, col0 = u.pn * BM + wc * 32 + 8 * fq;
;         u32x4 rv[8][2];
; #pragma unroll
;         for (int i = 0; i < 8; ++i)
; #pragma unroll
;             for (int bj = 0; bj < 2; ++bj) rv[i][bj] = *(const u32x4*)(Rin + (size_t)(row0 + (i >> 2) * HALF + (i & 3) * 16) * DMODEL + col0 + bj * HALF);
; #pragma unroll
;         for (int ai = 0; ai < 2; ++ai)
; #pragma unroll
;             for (int m = 0; m < 4; ++m) { const int row = row0 + ai * HALF + m * 16; float part = 0.f;
; #pragma unroll
;                 for (int bj = 0; bj < 2; ++bj) { f32x4 r0, r1; unpack8(rv[ai * 4 + m][bj], r0, r1);
;                     const f32x4 h0 = r0 + acc[ai][bj][m][0], h1 = r1 + acc[ai][bj][m][1]; part += sumsq8(h0, h1);
;                     *(u32x4*)(XBo + (size_t)row * DMODEL + col0 + bj * HALF) = pack8(h0, h1); }
;                 part += __shfl_xor(part, 16); part += __shfl_xor(part, 32);
;                 if (fq == 0) ssq[(size_t)row * 16 + u.pn * 4 + wc] = part; }
.LBB0_517:
	v_mov_b32_e32 v116, v192
	s_lshl_b32 s1, s40, 8
	v_readfirstlane_b32 s0, v116
	s_bfe_u32 s17, s0, 0x20006
	s_ashr_i32 s0, s0, 2
	s_andn2_b32 s0, s0, 63
	s_add_i32 s0, s0, s1
	v_and_or_b32 v216, v116, 15, s0
	s_lshl_b32 s0, s26, 8
	s_lshl_b32 s1, s17, 5
	v_bfe_u32 v249, v116, 4, 2
	s_or_b32 s0, s1, s0
	v_lshl_or_b32 v214, v249, 3, s0
	v_ashrrev_i32_e32 v215, 31, v214
	v_lshlrev_b64 v[234:235], 1, v[214:215]
	v_ashrrev_i32_e32 v217, 31, v216
	v_lshl_add_u64 v[120:121], s[6:7], 0, v[234:235]
	v_lshlrev_b64 v[236:237], 11, v[216:217]
	v_lshl_add_u64 v[116:117], v[120:121], 0, v[236:237]
	global_load_dwordx4 v[188:191], v[116:117], off
	global_load_dwordx4 v[184:187], v[116:117], off offset:256
	v_or_b32_e32 v230, 16, v216
	v_ashrrev_i32_e32 v231, 31, v230
	v_or_b32_e32 v226, 32, v216
	v_lshlrev_b64 v[232:233], 11, v[230:231]
	v_ashrrev_i32_e32 v227, 31, v226
	v_or_b32_e32 v222, 48, v216
	v_lshl_add_u64 v[116:117], v[120:121], 0, v[232:233]
	v_lshlrev_b64 v[228:229], 11, v[226:227]
	v_ashrrev_i32_e32 v223, 31, v222
	v_add_u32_e32 v218, 0x80, v216
	global_load_dwordx4 v[180:183], v[116:117], off
	global_load_dwordx4 v[176:179], v[116:117], off offset:256
	v_lshl_add_u64 v[116:117], v[120:121], 0, v[228:229]
	v_lshlrev_b64 v[224:225], 11, v[222:223]
	v_ashrrev_i32_e32 v219, 31, v218
	global_load_dwordx4 v[172:175], v[116:117], off
	global_load_dwordx4 v[168:171], v[116:117], off offset:256
	v_lshl_add_u64 v[116:117], v[120:121], 0, v[224:225]
	v_lshlrev_b64 v[220:221], 11, v[218:219]
	global_load_dwordx4 v[164:167], v[116:117], off
	global_load_dwordx4 v[160:163], v[116:117], off offset:256
	v_lshl_add_u64 v[116:117], v[120:121], 0, v[220:221]
	global_load_dwordx4 v[156:159], v[116:117], off
	global_load_dwordx4 v[144:147], v[116:117], off offset:256
	v_add_u32_e32 v116, 0x90, v216
	v_ashrrev_i32_e32 v117, 31, v116
	v_lshlrev_b64 v[116:117], 11, v[116:117]
	v_lshl_add_u64 v[116:117], v[120:121], 0, v[116:117]
	global_load_dwordx4 v[140:143], v[116:117], off
	global_load_dwordx4 v[136:139], v[116:117], off offset:256
	v_add_u32_e32 v116, 0xa0, v216
	v_add_u32_e32 v122, 0xb0, v216
	v_ashrrev_i32_e32 v117, 31, v116
	v_ashrrev_i32_e32 v123, 31, v122
	v_lshlrev_b64 v[116:117], 11, v[116:117]
	v_lshlrev_b64 v[122:123], 11, v[122:123]
	v_lshl_add_u64 v[116:117], v[120:121], 0, v[116:117]
	v_lshl_add_u64 v[120:121], v[120:121], 0, v[122:123]
	global_load_dwordx4 v[128:131], v[116:117], off
	s_nop 0
	global_load_dwordx4 v[116:119], v[116:117], off offset:256
	s_nop 0
	global_load_dwordx4 v[132:135], v[120:121], off
	s_nop 0
	global_load_dwordx4 v[120:123], v[120:121], off offset:256
	s_lshl_b32 s26, s26, 2
	v_cmp_eq_u32_e32 vcc, 0, v249
	s_ashr_i32 s27, s26, 31
	s_waitcnt vmcnt(14)
	v_lshlrev_b32_e32 v250, 16, v188
	v_and_b32_e32 v251, 0xffff0000, v188
	v_lshlrev_b32_e32 v188, 16, v189
	v_and_b32_e32 v189, 0xffff0000, v189
	v_lshlrev_b32_e32 v252, 16, v190
	v_and_b32_e32 v253, 0xffff0000, v190
	v_lshlrev_b32_e32 v190, 16, v191
	v_and_b32_e32 v191, 0xffff0000, v191
	v_pk_add_f32 v[154:155], v[154:155], v[188:189]
	v_pk_add_f32 v[152:153], v[152:153], v[250:251]
	v_pk_add_f32 v[188:189], v[150:151], v[190:191]
	v_pk_add_f32 v[150:151], v[148:149], v[252:253]
	v_mul_f32_e32 v148, v153, v153
	v_mul_f32_e32 v149, v155, v155
	v_fmac_f32_e32 v148, v152, v152
	v_fmac_f32_e32 v149, v154, v154
	v_add_f32_e32 v148, v148, v149
	v_mul_f32_e32 v149, v151, v151
	v_mul_f32_e32 v190, v189, v189
	v_fmac_f32_e32 v149, v150, v150
	v_fmac_f32_e32 v190, v188, v188
	v_add_f32_e32 v149, v149, v190
	v_add_f32_e32 v190, v148, v149
	v_cvt_pk_bf16_f32 v148, v152, v153
	v_lshl_add_u64 v[152:153], s[10:11], 0, v[236:237]
	v_cvt_pk_bf16_f32 v149, v154, v155
	v_cvt_pk_bf16_f32 v150, v150, v151
	v_cvt_pk_bf16_f32 v151, v188, v189
	v_lshl_add_u64 v[152:153], v[152:153], 0, v[234:235]
	global_store_dwordx4 v[152:153], v[148:151], off
	v_lshlrev_b32_e32 v154, 16, v186
	v_and_b32_e32 v155, 0xffff0000, v186
	v_lshlrev_b32_e32 v148, 16, v184
	v_and_b32_e32 v149, 0xffff0000, v184
	v_lshlrev_b32_e32 v150, 16, v185
	v_and_b32_e32 v151, 0xffff0000, v185
	v_lshlrev_b32_e32 v184, 16, v187
	v_and_b32_e32 v185, 0xffff0000, v187
	v_pk_add_f32 v[126:127], v[126:127], v[150:151]
	v_pk_add_f32 v[124:125], v[124:125], v[148:149]
	v_pk_add_f32 v[148:149], v[114:115], v[184:185]
	v_pk_add_f32 v[114:115], v[112:113], v[154:155]
	v_mul_f32_e32 v112, v125, v125
	v_mul_f32_e32 v113, v127, v127
	v_fmac_f32_e32 v112, v124, v124
	v_fmac_f32_e32 v113, v126, v126
	v_add_f32_e32 v112, v112, v113
	v_mul_f32_e32 v113, v115, v115
	v_mul_f32_e32 v150, v149, v149
	v_fmac_f32_e32 v113, v114, v114
	v_fmac_f32_e32 v150, v148, v148
	v_add_f32_e32 v113, v113, v150
	v_add_f32_e32 v112, v112, v113
	v_add_f32_e32 v150, v190, v112
	v_cvt_pk_bf16_f32 v112, v124, v125
	v_cvt_pk_bf16_f32 v113, v126, v127
	v_cvt_pk_bf16_f32 v114, v114, v115
	v_cvt_pk_bf16_f32 v115, v148, v149
	global_store_dwordx4 v[152:153], v[112:115], off offset:256
	s_nop 1
	v_and_b32_e32 v113, 64, v241
	v_xor_b32_e32 v112, 16, v241
	v_add_u32_e32 v113, 64, v113
	v_cmp_lt_i32_e64 s[0:1], v112, v113
	v_xor_b32_e32 v115, 32, v241
	s_nop 0
	v_cndmask_b32_e64 v112, v241, v112, s[0:1]
	v_lshlrev_b32_e32 v112, 2, v112
	ds_bpermute_b32 v114, v112, v150
	v_cmp_lt_i32_e64 s[0:1], v115, v113
	s_waitcnt lgkmcnt(0)
	v_add_f32_e32 v114, v150, v114
	v_cndmask_b32_e64 v113, v241, v115, s[0:1]
	v_lshlrev_b32_e32 v113, 2, v113
	ds_bpermute_b32 v115, v113, v114
	s_and_saveexec_b64 s[0:1], vcc
	s_cbranch_execz .LBB0_519
	v_lshlrev_b64 v[124:125], 6, v[216:217]
	v_lshl_add_u64 v[124:125], s[12:13], 0, v[124:125]
	v_lshl_add_u64 v[124:125], s[26:27], 2, v[124:125]
	s_lshl_b32 s72, s17, 2
	v_lshl_add_u64 v[124:125], v[124:125], 0, s[72:73]
	s_waitcnt lgkmcnt(0)
	v_add_f32_e32 v114, v114, v115
	global_store_dword v[124:125], v114, off
; __device__ __forceinline__ u32x4 pack8(const f32x4 v0, const f32x4 v1) { u32x4 w; w.x = cvt_pk_bf16(v0[0], v0[1]); w.y = cvt_pk_bf16(v0[2], v0[3]); w.z = cvt_pk_bf16(v1[0], v1[1]); w.w = cvt_pk_bf16(v1[2], v1[3]); return w; }
; __device__ __forceinline__ float sumsq8(const f32x4 a, const f32x4 b) { return ((a[0] * a[0] + a[1] * a[1]) + (a[2] * a[2] + a[3] * a[3])) + ((b[0] * b[0] + b[1] * b[1]) + (b[2] * b[2] + b[3] * b[3])); }
; __device__ __forceinline__ void unpack8(const u32x4 w, f32x4& a, f32x4& b) { a = (f32x4){bf_lo(w.x), bf_hi(w.x), bf_lo(w.y), bf_hi(w.y)}; b = (f32x4){bf_lo(w.z), bf_hi(w.z), bf_lo(w.w), bf_hi(w.w)}; }
;     __device__ __forceinline__ void operator()(const f32x4 (&acc)[2][2][4][2], const Unit& u, int wr, int wc, int fr, int fq) const {
;     ...
;         for (int ai = 0; ai < 2; ++ai)
; #pragma unroll
;             for (int m = 0; m < 4; ++m) { const int row = row0 + ai * HALF + m * 16; float part = 0.f;
; #pragma unroll
;                 for (int bj = 0; bj < 2; ++bj) { f32x4 r0, r1; unpack8(rv[ai * 4 + m][bj], r0, r1);
;                     const f32x4 h0 = r0 + acc[ai][bj][m][0], h1 = r1 + acc[ai][bj][m][1]; part += sumsq8(h0, h1);
;                     *(u32x4*)(XBo + (size_t)row * DMODEL + col0 + bj * HALF) = pack8(h0, h1); }
;                 part += __shfl_xor(part, 16); part += __shfl_xor(part, 32);
;                 if (fq == 0) ssq[(size_t)row * 16 + u.pn * 4 + wc] = part; }
.LBB0_519:
	s_or_b64 exec, exec, s[0:1]
	s_waitcnt vmcnt(15)
	v_lshlrev_b32_e32 v114, 16, v180
	s_waitcnt lgkmcnt(0)
	v_and_b32_e32 v115, 0xffff0000, v180
	v_lshlrev_b32_e32 v124, 16, v181
	v_and_b32_e32 v125, 0xffff0000, v181
	v_lshlrev_b32_e32 v126, 16, v182
	v_and_b32_e32 v127, 0xffff0000, v182
	v_lshlrev_b32_e32 v148, 16, v183
	v_and_b32_e32 v149, 0xffff0000, v183
	v_pk_add_f32 v[110:111], v[110:111], v[124:125]
	v_pk_add_f32 v[108:109], v[108:109], v[114:115]
	v_pk_add_f32 v[114:115], v[106:107], v[148:149]
	v_pk_add_f32 v[106:107], v[104:105], v[126:127]
	v_mul_f32_e32 v104, v109, v109
	v_mul_f32_e32 v105, v111, v111
	v_fmac_f32_e32 v104, v108, v108
	v_fmac_f32_e32 v105, v110, v110
	v_add_f32_e32 v104, v104, v105
	v_mul_f32_e32 v105, v107, v107
	v_mul_f32_e32 v124, v115, v115
	v_fmac_f32_e32 v105, v106, v106
	v_fmac_f32_e32 v124, v114, v114
	v_add_f32_e32 v105, v105, v124
	v_add_f32_e32 v126, v104, v105
	v_cvt_pk_bf16_f32 v104, v108, v109
	v_cvt_pk_bf16_f32 v105, v110, v111
	v_lshlrev_b32_e32 v108, 16, v176
	v_and_b32_e32 v109, 0xffff0000, v176
	v_lshlrev_b32_e32 v110, 16, v177
	v_and_b32_e32 v111, 0xffff0000, v177
	v_cvt_pk_bf16_f32 v106, v106, v107
	v_cvt_pk_bf16_f32 v107, v114, v115
	v_lshlrev_b32_e32 v114, 16, v178
	v_and_b32_e32 v115, 0xffff0000, v178
	v_pk_add_f32 v[102:103], v[102:103], v[110:111]
	v_pk_add_f32 v[100:101], v[100:101], v[108:109]
	v_lshlrev_b32_e32 v124, 16, v179
	v_and_b32_e32 v125, 0xffff0000, v179
	v_pk_add_f32 v[110:111], v[96:97], v[114:115]
	v_mul_f32_e32 v96, v101, v101
	v_mul_f32_e32 v97, v103, v103
	v_pk_add_f32 v[108:109], v[98:99], v[124:125]
	v_fmac_f32_e32 v96, v100, v100
	v_fmac_f32_e32 v97, v102, v102
	v_add_f32_e32 v96, v96, v97
	v_mul_f32_e32 v97, v111, v111
	v_mul_f32_e32 v98, v109, v109
	v_fmac_f32_e32 v97, v110, v110
	v_fmac_f32_e32 v98, v108, v108
	v_add_f32_e32 v97, v97, v98
	v_add_f32_e32 v96, v96, v97
	v_add_f32_e32 v99, v126, v96
	ds_bpermute_b32 v124, v112, v99
	v_lshl_add_u64 v[96:97], s[10:11], 0, v[232:233]
	v_lshl_add_u64 v[114:115], v[214:215], 1, v[96:97]
	global_store_dwordx4 v[114:115], v[104:107], off
	v_cvt_pk_bf16_f32 v98, v100, v101
	s_waitcnt lgkmcnt(0)
	v_add_f32_e32 v96, v99, v124
	ds_bpermute_b32 v97, v113, v96
	v_cvt_pk_bf16_f32 v99, v102, v103
	v_cvt_pk_bf16_f32 v100, v110, v111
	v_cvt_pk_bf16_f32 v101, v108, v109
	global_store_dwordx4 v[114:115], v[98:101], off offset:256
	s_and_saveexec_b64 s[0:1], vcc
	s_cbranch_execz .LBB0_521
	v_lshlrev_b64 v[98:99], 6, v[230:231]
	v_lshl_add_u64 v[98:99], s[12:13], 0, v[98:99]
	v_lshl_add_u64 v[98:99], s[26:27], 2, v[98:99]
	s_lshl_b32 s72, s17, 2
	v_lshl_add_u64 v[98:99], v[98:99], 0, s[72:73]
	s_waitcnt lgkmcnt(0)
	v_add_f32_e32 v96, v96, v97
	global_store_dword v[98:99], v96, off
.LBB0_521:
	s_or_b64 exec, exec, s[0:1]
	s_waitcnt vmcnt(16)
	v_lshlrev_b32_e32 v96, 16, v172
	s_waitcnt lgkmcnt(0)
	v_and_b32_e32 v97, 0xffff0000, v172
	v_lshlrev_b32_e32 v98, 16, v173
	v_and_b32_e32 v99, 0xffff0000, v173
	v_lshlrev_b32_e32 v100, 16, v174
	v_and_b32_e32 v101, 0xffff0000, v174
	v_lshlrev_b32_e32 v102, 16, v175
	v_and_b32_e32 v103, 0xffff0000, v175
	v_pk_add_f32 v[94:95], v[94:95], v[98:99]
	v_pk_add_f32 v[92:93], v[92:93], v[96:97]
	v_pk_add_f32 v[96:97], v[90:91], v[102:103]
	v_pk_add_f32 v[90:91], v[88:89], v[100:101]
	v_mul_f32_e32 v88, v93, v93
	v_mul_f32_e32 v89, v95, v95
	v_fmac_f32_e32 v88, v92, v92
	v_fmac_f32_e32 v89, v94, v94
	v_add_f32_e32 v88, v88, v89
	v_mul_f32_e32 v89, v91, v91
	v_mul_f32_e32 v98, v97, v97
	v_fmac_f32_e32 v89, v90, v90
	v_fmac_f32_e32 v98, v96, v96
	v_add_f32_e32 v89, v89, v98
	v_add_f32_e32 v100, v88, v89
	v_cvt_pk_bf16_f32 v88, v92, v93
	v_cvt_pk_bf16_f32 v89, v94, v95
	v_lshlrev_b32_e32 v92, 16, v168
	v_and_b32_e32 v93, 0xffff0000, v168
	v_lshlrev_b32_e32 v94, 16, v169
	v_and_b32_e32 v95, 0xffff0000, v169
	v_cvt_pk_bf16_f32 v90, v90, v91
	v_cvt_pk_bf16_f32 v91, v96, v97
	v_lshlrev_b32_e32 v96, 16, v170
	v_and_b32_e32 v97, 0xffff0000, v170
	v_pk_add_f32 v[86:87], v[86:87], v[94:95]
	v_pk_add_f32 v[84:85], v[84:85], v[92:93]
	v_lshlrev_b32_e32 v98, 16, v171
	v_and_b32_e32 v99, 0xffff0000, v171
	v_pk_add_f32 v[94:95], v[80:81], v[96:97]
	v_mul_f32_e32 v80, v85, v85
	v_mul_f32_e32 v81, v87, v87
	v_pk_add_f32 v[92:93], v[82:83], v[98:99]
	v_fmac_f32_e32 v80, v84, v84
	v_fmac_f32_e32 v81, v86, v86
	v_add_f32_e32 v80, v80, v81
	v_mul_f32_e32 v81, v95, v95
	v_mul_f32_e32 v82, v93, v93
	v_fmac_f32_e32 v81, v94, v94
	v_fmac_f32_e32 v82, v92, v92
	v_add_f32_e32 v81, v81, v82
	v_add_f32_e32 v80, v80, v81
	v_add_f32_e32 v83, v100, v80
	ds_bpermute_b32 v98, v112, v83
	v_lshl_add_u64 v[80:81], s[10:11], 0, v[228:229]
	v_lshl_add_u64 v[96:97], v[214:215], 1, v[80:81]
	global_store_dwordx4 v[96:97], v[88:91], off
	v_cvt_pk_bf16_f32 v82, v84, v85
	s_waitcnt lgkmcnt(0)
	v_add_f32_e32 v80, v83, v98
	ds_bpermute_b32 v81, v113, v80
	v_cvt_pk_bf16_f32 v83, v86, v87
	v_cvt_pk_bf16_f32 v84, v94, v95
	v_cvt_pk_bf16_f32 v85, v92, v93
	global_store_dwordx4 v[96:97], v[82:85], off offset:256
	s_and_saveexec_b64 s[0:1], vcc
	s_cbranch_execz .LBB0_523
	v_lshlrev_b64 v[82:83], 6, v[226:227]
	v_lshl_add_u64 v[82:83], s[12:13], 0, v[82:83]
	v_lshl_add_u64 v[82:83], s[26:27], 2, v[82:83]
	s_lshl_b32 s72, s17, 2
	v_lshl_add_u64 v[82:83], v[82:83], 0, s[72:73]
	s_waitcnt lgkmcnt(0)
	v_add_f32_e32 v80, v80, v81
	global_store_dword v[82:83], v80, off
; __device__ __forceinline__ u32x4 pack8(const f32x4 v0, const f32x4 v1) { u32x4 w; w.x = cvt_pk_bf16(v0[0], v0[1]); w.y = cvt_pk_bf16(v0[2], v0[3]); w.z = cvt_pk_bf16(v1[0], v1[1]); w.w = cvt_pk_bf16(v1[2], v1[3]); return w; }
; __device__ __forceinline__ float sumsq8(const f32x4 a, const f32x4 b) { return ((a[0] * a[0] + a[1] * a[1]) + (a[2] * a[2] + a[3] * a[3])) + ((b[0] * b[0] + b[1] * b[1]) + (b[2] * b[2] + b[3] * b[3])); }
; __device__ __forceinline__ void unpack8(const u32x4 w, f32x4& a, f32x4& b) { a = (f32x4){bf_lo(w.x), bf_hi(w.x), bf_lo(w.y), bf_hi(w.y)}; b = (f32x4){bf_lo(w.z), bf_hi(w.z), bf_lo(w.w), bf_hi(w.w)}; }
;     __device__ __forceinline__ void operator()(const f32x4 (&acc)[2][2][4][2], const Unit& u, int wr, int wc, int fr, int fq) const {
;     ...
;         for (int ai = 0; ai < 2; ++ai)
; #pragma unroll
;             for (int m = 0; m < 4; ++m) { const int row = row0 + ai * HALF + m * 16; float part = 0.f;
; #pragma unroll
;                 for (int bj = 0; bj < 2; ++bj) { f32x4 r0, r1; unpack8(rv[ai * 4 + m][bj], r0, r1);
;                     const f32x4 h0 = r0 + acc[ai][bj][m][0], h1 = r1 + acc[ai][bj][m][1]; part += sumsq8(h0, h1);
;                     *(u32x4*)(XBo + (size_t)row * DMODEL + col0 + bj * HALF) = pack8(h0, h1); }
;                 part += __shfl_xor(part, 16); part += __shfl_xor(part, 32);
;                 if (fq == 0) ssq[(size_t)row * 16 + u.pn * 4 + wc] = part; }
.LBB0_523:
	s_or_b64 exec, exec, s[0:1]
	s_waitcnt vmcnt(17)
	v_lshlrev_b32_e32 v80, 16, v164
	s_waitcnt lgkmcnt(0)
	v_and_b32_e32 v81, 0xffff0000, v164
	v_lshlrev_b32_e32 v82, 16, v165
	v_and_b32_e32 v83, 0xffff0000, v165
	v_lshlrev_b32_e32 v84, 16, v166
	v_and_b32_e32 v85, 0xffff0000, v166
	v_lshlrev_b32_e32 v86, 16, v167
	v_and_b32_e32 v87, 0xffff0000, v167
	v_pk_add_f32 v[78:79], v[78:79], v[82:83]
	v_pk_add_f32 v[76:77], v[76:77], v[80:81]
	v_pk_add_f32 v[80:81], v[74:75], v[86:87]
	v_pk_add_f32 v[74:75], v[72:73], v[84:85]
	v_mul_f32_e32 v72, v77, v77
	v_mul_f32_e32 v73, v79, v79
	v_fmac_f32_e32 v72, v76, v76
	v_fmac_f32_e32 v73, v78, v78
	v_add_f32_e32 v72, v72, v73
	v_mul_f32_e32 v73, v75, v75
	v_mul_f32_e32 v82, v81, v81
	v_fmac_f32_e32 v73, v74, v74
	v_fmac_f32_e32 v82, v80, v80
	v_add_f32_e32 v73, v73, v82
	v_add_f32_e32 v84, v72, v73
	v_cvt_pk_bf16_f32 v72, v76, v77
	v_cvt_pk_bf16_f32 v73, v78, v79
	v_lshlrev_b32_e32 v76, 16, v160
	v_and_b32_e32 v77, 0xffff0000, v160
	v_lshlrev_b32_e32 v78, 16, v161
	v_and_b32_e32 v79, 0xffff0000, v161
	v_cvt_pk_bf16_f32 v74, v74, v75
	v_cvt_pk_bf16_f32 v75, v80, v81
	v_lshlrev_b32_e32 v80, 16, v162
	v_and_b32_e32 v81, 0xffff0000, v162
	v_pk_add_f32 v[70:71], v[70:71], v[78:79]
	v_pk_add_f32 v[68:69], v[68:69], v[76:77]
	v_lshlrev_b32_e32 v82, 16, v163
	v_and_b32_e32 v83, 0xffff0000, v163
	v_pk_add_f32 v[78:79], v[64:65], v[80:81]
	v_mul_f32_e32 v64, v69, v69
	v_mul_f32_e32 v65, v71, v71
	v_pk_add_f32 v[76:77], v[66:67], v[82:83]
	v_fmac_f32_e32 v64, v68, v68
	v_fmac_f32_e32 v65, v70, v70
	v_add_f32_e32 v64, v64, v65
	v_mul_f32_e32 v65, v79, v79
	v_mul_f32_e32 v66, v77, v77
	v_fmac_f32_e32 v65, v78, v78
	v_fmac_f32_e32 v66, v76, v76
	v_add_f32_e32 v65, v65, v66
	v_add_f32_e32 v64, v64, v65
	v_add_f32_e32 v67, v84, v64
	ds_bpermute_b32 v82, v112, v67
	v_lshl_add_u64 v[64:65], s[10:11], 0, v[224:225]
	v_lshl_add_u64 v[80:81], v[214:215], 1, v[64:65]
	global_store_dwordx4 v[80:81], v[72:75], off
	v_cvt_pk_bf16_f32 v66, v68, v69
	s_waitcnt lgkmcnt(0)
	v_add_f32_e32 v64, v67, v82
	ds_bpermute_b32 v65, v113, v64
	v_cvt_pk_bf16_f32 v67, v70, v71
	v_cvt_pk_bf16_f32 v68, v78, v79
	v_cvt_pk_bf16_f32 v69, v76, v77
	global_store_dwordx4 v[80:81], v[66:69], off offset:256
	s_and_saveexec_b64 s[0:1], vcc
	s_cbranch_execz .LBB0_525
	v_lshlrev_b64 v[66:67], 6, v[222:223]
	v_lshl_add_u64 v[66:67], s[12:13], 0, v[66:67]
	v_lshl_add_u64 v[66:67], s[26:27], 2, v[66:67]
	s_lshl_b32 s72, s17, 2
	v_lshl_add_u64 v[66:67], v[66:67], 0, s[72:73]
	s_waitcnt lgkmcnt(0)
	v_add_f32_e32 v64, v64, v65
	global_store_dword v[66:67], v64, off
.LBB0_525:
	s_or_b64 exec, exec, s[0:1]
	s_waitcnt vmcnt(18)
	v_lshlrev_b32_e32 v64, 16, v156
	s_waitcnt lgkmcnt(0)
	v_and_b32_e32 v65, 0xffff0000, v156
	v_lshlrev_b32_e32 v66, 16, v157
	v_and_b32_e32 v67, 0xffff0000, v157
	v_lshlrev_b32_e32 v68, 16, v158
	v_and_b32_e32 v69, 0xffff0000, v158
	v_lshlrev_b32_e32 v70, 16, v159
	v_and_b32_e32 v71, 0xffff0000, v159
	v_pk_add_f32 v[62:63], v[62:63], v[66:67]
	v_pk_add_f32 v[60:61], v[60:61], v[64:65]
	v_pk_add_f32 v[64:65], v[58:59], v[70:71]
	v_pk_add_f32 v[58:59], v[56:57], v[68:69]
	v_mul_f32_e32 v56, v61, v61
	v_mul_f32_e32 v57, v63, v63
	v_fmac_f32_e32 v56, v60, v60
	v_fmac_f32_e32 v57, v62, v62
	v_add_f32_e32 v56, v56, v57
	v_mul_f32_e32 v57, v59, v59
	v_mul_f32_e32 v66, v65, v65
	v_fmac_f32_e32 v57, v58, v58
	v_fmac_f32_e32 v66, v64, v64
	v_add_f32_e32 v57, v57, v66
	v_add_f32_e32 v68, v56, v57
	v_cvt_pk_bf16_f32 v56, v60, v61
	v_cvt_pk_bf16_f32 v57, v62, v63
	v_lshlrev_b32_e32 v60, 16, v144
	v_and_b32_e32 v61, 0xffff0000, v144
	v_lshlrev_b32_e32 v62, 16, v145
	v_and_b32_e32 v63, 0xffff0000, v145
	v_cvt_pk_bf16_f32 v58, v58, v59
	v_cvt_pk_bf16_f32 v59, v64, v65
	v_lshlrev_b32_e32 v64, 16, v146
	v_and_b32_e32 v65, 0xffff0000, v146
	v_pk_add_f32 v[54:55], v[54:55], v[62:63]
	v_pk_add_f32 v[52:53], v[52:53], v[60:61]
	v_lshlrev_b32_e32 v66, 16, v147
	v_and_b32_e32 v67, 0xffff0000, v147
	v_pk_add_f32 v[62:63], v[48:49], v[64:65]
	v_mul_f32_e32 v48, v53, v53
	v_mul_f32_e32 v49, v55, v55
	v_pk_add_f32 v[60:61], v[50:51], v[66:67]
	v_fmac_f32_e32 v48, v52, v52
	v_fmac_f32_e32 v49, v54, v54
	v_add_f32_e32 v48, v48, v49
	v_mul_f32_e32 v49, v63, v63
	v_mul_f32_e32 v50, v61, v61
	v_fmac_f32_e32 v49, v62, v62
	v_fmac_f32_e32 v50, v60, v60
	v_add_f32_e32 v49, v49, v50
	v_add_f32_e32 v48, v48, v49
	v_add_f32_e32 v51, v68, v48
	ds_bpermute_b32 v66, v112, v51
	v_lshl_add_u64 v[48:49], s[10:11], 0, v[220:221]
	v_lshl_add_u64 v[64:65], v[214:215], 1, v[48:49]
	global_store_dwordx4 v[64:65], v[56:59], off
	v_cvt_pk_bf16_f32 v50, v52, v53
	s_waitcnt lgkmcnt(0)
	v_add_f32_e32 v48, v51, v66
	ds_bpermute_b32 v49, v113, v48
	v_cvt_pk_bf16_f32 v51, v54, v55
	v_cvt_pk_bf16_f32 v52, v62, v63
	v_cvt_pk_bf16_f32 v53, v60, v61
	global_store_dwordx4 v[64:65], v[50:53], off offset:256
	s_and_saveexec_b64 s[0:1], vcc
	s_cbranch_execz .LBB0_527
	v_lshlrev_b64 v[50:51], 6, v[218:219]
	v_lshl_add_u64 v[50:51], s[12:13], 0, v[50:51]
	v_lshl_add_u64 v[50:51], s[26:27], 2, v[50:51]
	s_lshl_b32 s72, s17, 2
	v_lshl_add_u64 v[50:51], v[50:51], 0, s[72:73]
	s_waitcnt lgkmcnt(0)
	v_add_f32_e32 v48, v48, v49
	global_store_dword v[50:51], v48, off
; __device__ __forceinline__ u32x4 pack8(const f32x4 v0, const f32x4 v1) { u32x4 w; w.x = cvt_pk_bf16(v0[0], v0[1]); w.y = cvt_pk_bf16(v0[2], v0[3]); w.z = cvt_pk_bf16(v1[0], v1[1]); w.w = cvt_pk_bf16(v1[2], v1[3]); return w; }
; __device__ __forceinline__ float sumsq8(const f32x4 a, const f32x4 b) { return ((a[0] * a[0] + a[1] * a[1]) + (a[2] * a[2] + a[3] * a[3])) + ((b[0] * b[0] + b[1] * b[1]) + (b[2] * b[2] + b[3] * b[3])); }
; __device__ __forceinline__ void unpack8(const u32x4 w, f32x4& a, f32x4& b) { a = (f32x4){bf_lo(w.x), bf_hi(w.x), bf_lo(w.y), bf_hi(w.y)}; b = (f32x4){bf_lo(w.z), bf_hi(w.z), bf_lo(w.w), bf_hi(w.w)}; }
;     __device__ __forceinline__ void operator()(const f32x4 (&acc)[2][2][4][2], const Unit& u, int wr, int wc, int fr, int fq) const {
;     ...
;         for (int ai = 0; ai < 2; ++ai)
; #pragma unroll
;             for (int m = 0; m < 4; ++m) { const int row = row0 + ai * HALF + m * 16; float part = 0.f;
; #pragma unroll
;                 for (int bj = 0; bj < 2; ++bj) { f32x4 r0, r1; unpack8(rv[ai * 4 + m][bj], r0, r1);
;                     const f32x4 h0 = r0 + acc[ai][bj][m][0], h1 = r1 + acc[ai][bj][m][1]; part += sumsq8(h0, h1);
;                     *(u32x4*)(XBo + (size_t)row * DMODEL + col0 + bj * HALF) = pack8(h0, h1); }
;                 part += __shfl_xor(part, 16); part += __shfl_xor(part, 32);
;                 if (fq == 0) ssq[(size_t)row * 16 + u.pn * 4 + wc] = part; }
.LBB0_527:
	s_or_b64 exec, exec, s[0:1]
	s_waitcnt vmcnt(19)
	v_lshlrev_b32_e32 v52, 16, v140
	v_and_b32_e32 v53, 0xffff0000, v140
	v_lshlrev_b32_e32 v54, 16, v141
	v_and_b32_e32 v55, 0xffff0000, v141
	v_lshlrev_b32_e32 v56, 16, v142
	v_and_b32_e32 v57, 0xffff0000, v142
	v_lshlrev_b32_e32 v58, 16, v143
	v_and_b32_e32 v59, 0xffff0000, v143
	v_pk_add_f32 v[46:47], v[46:47], v[54:55]
	v_pk_add_f32 v[44:45], v[44:45], v[52:53]
	v_pk_add_f32 v[52:53], v[42:43], v[58:59]
	v_pk_add_f32 v[42:43], v[40:41], v[56:57]
	v_mul_f32_e32 v40, v45, v45
	v_mul_f32_e32 v41, v47, v47
	v_fmac_f32_e32 v40, v44, v44
	v_fmac_f32_e32 v41, v46, v46
	v_add_f32_e32 v40, v40, v41
	v_mul_f32_e32 v41, v43, v43
	v_mul_f32_e32 v54, v53, v53
	v_fmac_f32_e32 v41, v42, v42
	v_fmac_f32_e32 v54, v52, v52
	v_add_f32_e32 v41, v41, v54
	v_add_f32_e32 v56, v40, v41
	v_cvt_pk_bf16_f32 v40, v44, v45
	v_cvt_pk_bf16_f32 v41, v46, v47
	v_lshlrev_b32_e32 v44, 16, v136
	v_and_b32_e32 v45, 0xffff0000, v136
	v_lshlrev_b32_e32 v46, 16, v137
	v_and_b32_e32 v47, 0xffff0000, v137
	v_cvt_pk_bf16_f32 v42, v42, v43
	v_cvt_pk_bf16_f32 v43, v52, v53
	v_lshlrev_b32_e32 v52, 16, v138
	v_and_b32_e32 v53, 0xffff0000, v138
	v_pk_add_f32 v[38:39], v[38:39], v[46:47]
	v_pk_add_f32 v[36:37], v[36:37], v[44:45]
	v_lshlrev_b32_e32 v54, 16, v139
	v_and_b32_e32 v55, 0xffff0000, v139
	v_pk_add_f32 v[46:47], v[32:33], v[52:53]
	v_mul_f32_e32 v32, v37, v37
	v_mul_f32_e32 v33, v39, v39
	v_pk_add_f32 v[44:45], v[34:35], v[54:55]
	v_fmac_f32_e32 v32, v36, v36
	v_fmac_f32_e32 v33, v38, v38
	v_add_f32_e32 v32, v32, v33
	v_mul_f32_e32 v33, v47, v47
	v_mul_f32_e32 v34, v45, v45
	v_fmac_f32_e32 v33, v46, v46
	v_fmac_f32_e32 v34, v44, v44
	v_add_f32_e32 v33, v33, v34
	v_add_f32_e32 v32, v32, v33
	v_add_f32_e32 v35, v56, v32
	ds_bpermute_b32 v52, v112, v35
	v_add_u32_e32 v48, 0x90, v216
	s_waitcnt lgkmcnt(1)
	v_ashrrev_i32_e32 v49, 31, v48
	v_lshlrev_b64 v[50:51], 11, v[48:49]
	v_lshl_add_u64 v[32:33], s[10:11], 0, v[50:51]
	v_lshl_add_u64 v[50:51], v[214:215], 1, v[32:33]
	s_waitcnt lgkmcnt(0)
	v_add_f32_e32 v32, v35, v52
	ds_bpermute_b32 v33, v113, v32
	global_store_dwordx4 v[50:51], v[40:43], off
	v_cvt_pk_bf16_f32 v34, v36, v37
	v_cvt_pk_bf16_f32 v35, v38, v39
	v_cvt_pk_bf16_f32 v36, v46, v47
	v_cvt_pk_bf16_f32 v37, v44, v45
	global_store_dwordx4 v[50:51], v[34:37], off offset:256
	s_and_saveexec_b64 s[0:1], vcc
	s_cbranch_execz .LBB0_529
	v_lshlrev_b64 v[34:35], 6, v[48:49]
	v_lshl_add_u64 v[34:35], s[12:13], 0, v[34:35]
	v_lshl_add_u64 v[34:35], s[26:27], 2, v[34:35]
	s_lshl_b32 s72, s17, 2
	v_lshl_add_u64 v[34:35], v[34:35], 0, s[72:73]
	s_waitcnt lgkmcnt(0)
	v_add_f32_e32 v32, v32, v33
	global_store_dword v[34:35], v32, off
; __device__ __forceinline__ u32x4 pack8(const f32x4 v0, const f32x4 v1) { u32x4 w; w.x = cvt_pk_bf16(v0[0], v0[1]); w.y = cvt_pk_bf16(v0[2], v0[3]); w.z = cvt_pk_bf16(v1[0], v1[1]); w.w = cvt_pk_bf16(v1[2], v1[3]); return w; }
; __device__ __forceinline__ float sumsq8(const f32x4 a, const f32x4 b) { return ((a[0] * a[0] + a[1] * a[1]) + (a[2] * a[2] + a[3] * a[3])) + ((b[0] * b[0] + b[1] * b[1]) + (b[2] * b[2] + b[3] * b[3])); }
; __device__ __forceinline__ void unpack8(const u32x4 w, f32x4& a, f32x4& b) { a = (f32x4){bf_lo(w.x), bf_hi(w.x), bf_lo(w.y), bf_hi(w.y)}; b = (f32x4){bf_lo(w.z), bf_hi(w.z), bf_lo(w.w), bf_hi(w.w)}; }
;     __device__ __forceinline__ void operator()(const f32x4 (&acc)[2][2][4][2], const Unit& u, int wr, int wc, int fr, int fq) const {
;     ...
;         for (int ai = 0; ai < 2; ++ai)
; #pragma unroll
;             for (int m = 0; m < 4; ++m) { const int row = row0 + ai * HALF + m * 16; float part = 0.f;
; #pragma unroll
;                 for (int bj = 0; bj < 2; ++bj) { f32x4 r0, r1; unpack8(rv[ai * 4 + m][bj], r0, r1);
;                     const f32x4 h0 = r0 + acc[ai][bj][m][0], h1 = r1 + acc[ai][bj][m][1]; part += sumsq8(h0, h1);
;                     *(u32x4*)(XBo + (size_t)row * DMODEL + col0 + bj * HALF) = pack8(h0, h1); }
;                 part += __shfl_xor(part, 16); part += __shfl_xor(part, 32);
;                 if (fq == 0) ssq[(size_t)row * 16 + u.pn * 4 + wc] = part; }
.LBB0_529:
	s_or_b64 exec, exec, s[0:1]
	s_waitcnt vmcnt(20)
	v_lshlrev_b32_e32 v36, 16, v128
	v_and_b32_e32 v37, 0xffff0000, v128
	v_lshlrev_b32_e32 v38, 16, v129
	v_and_b32_e32 v39, 0xffff0000, v129
	v_lshlrev_b32_e32 v40, 16, v130
	v_and_b32_e32 v41, 0xffff0000, v130
	v_lshlrev_b32_e32 v42, 16, v131
	v_and_b32_e32 v43, 0xffff0000, v131
	v_pk_add_f32 v[30:31], v[30:31], v[38:39]
	v_pk_add_f32 v[28:29], v[28:29], v[36:37]
	v_pk_add_f32 v[36:37], v[26:27], v[42:43]
	v_pk_add_f32 v[26:27], v[24:25], v[40:41]
	v_mul_f32_e32 v24, v29, v29
	v_mul_f32_e32 v25, v31, v31
	v_fmac_f32_e32 v24, v28, v28
	v_fmac_f32_e32 v25, v30, v30
	v_add_f32_e32 v24, v24, v25
	v_mul_f32_e32 v25, v27, v27
	v_mul_f32_e32 v38, v37, v37
	v_fmac_f32_e32 v25, v26, v26
	v_fmac_f32_e32 v38, v36, v36
	v_add_f32_e32 v25, v25, v38
	v_add_f32_e32 v40, v24, v25
	v_cvt_pk_bf16_f32 v24, v28, v29
	v_cvt_pk_bf16_f32 v25, v30, v31
	v_lshlrev_b32_e32 v28, 16, v116
	v_and_b32_e32 v29, 0xffff0000, v116
	v_lshlrev_b32_e32 v30, 16, v117
	v_and_b32_e32 v31, 0xffff0000, v117
	v_cvt_pk_bf16_f32 v26, v26, v27
	v_cvt_pk_bf16_f32 v27, v36, v37
	v_lshlrev_b32_e32 v36, 16, v118
	v_and_b32_e32 v37, 0xffff0000, v118
	v_pk_add_f32 v[22:23], v[22:23], v[30:31]
	v_pk_add_f32 v[20:21], v[20:21], v[28:29]
	v_lshlrev_b32_e32 v38, 16, v119
	v_and_b32_e32 v39, 0xffff0000, v119
	v_pk_add_f32 v[30:31], v[16:17], v[36:37]
	v_mul_f32_e32 v16, v21, v21
	v_mul_f32_e32 v17, v23, v23
	v_pk_add_f32 v[28:29], v[18:19], v[38:39]
	v_fmac_f32_e32 v16, v20, v20
	v_fmac_f32_e32 v17, v22, v22
	v_add_f32_e32 v16, v16, v17
	v_mul_f32_e32 v17, v31, v31
	v_mul_f32_e32 v18, v29, v29
	v_fmac_f32_e32 v17, v30, v30
	v_fmac_f32_e32 v18, v28, v28
	v_add_f32_e32 v17, v17, v18
	v_add_f32_e32 v16, v16, v17
	v_add_f32_e32 v19, v40, v16
	ds_bpermute_b32 v36, v112, v19
	v_add_u32_e32 v32, 0xa0, v216
	s_waitcnt lgkmcnt(1)
	v_ashrrev_i32_e32 v33, 31, v32
	v_lshlrev_b64 v[34:35], 11, v[32:33]
	v_lshl_add_u64 v[16:17], s[10:11], 0, v[34:35]
	v_lshl_add_u64 v[34:35], v[214:215], 1, v[16:17]
	s_waitcnt lgkmcnt(0)
	v_add_f32_e32 v16, v19, v36
	ds_bpermute_b32 v17, v113, v16
	global_store_dwordx4 v[34:35], v[24:27], off
	v_cvt_pk_bf16_f32 v18, v20, v21
	v_cvt_pk_bf16_f32 v19, v22, v23
	v_cvt_pk_bf16_f32 v20, v30, v31
	v_cvt_pk_bf16_f32 v21, v28, v29
	global_store_dwordx4 v[34:35], v[18:21], off offset:256
	s_and_saveexec_b64 s[0:1], vcc
	s_cbranch_execz .LBB0_531
	v_lshlrev_b64 v[18:19], 6, v[32:33]
	v_lshl_add_u64 v[18:19], s[12:13], 0, v[18:19]
	v_lshl_add_u64 v[18:19], s[26:27], 2, v[18:19]
	s_lshl_b32 s72, s17, 2
	v_lshl_add_u64 v[18:19], v[18:19], 0, s[72:73]
	s_waitcnt lgkmcnt(0)
	v_add_f32_e32 v16, v16, v17
	global_store_dword v[18:19], v16, off
.LBB0_531:
	s_or_b64 exec, exec, s[0:1]
	s_waitcnt vmcnt(21)
	v_lshlrev_b32_e32 v20, 16, v132
	v_and_b32_e32 v21, 0xffff0000, v132
	v_lshlrev_b32_e32 v22, 16, v133
	v_and_b32_e32 v23, 0xffff0000, v133
	v_lshlrev_b32_e32 v24, 16, v134
	v_and_b32_e32 v25, 0xffff0000, v134
	v_lshlrev_b32_e32 v26, 16, v135
	v_and_b32_e32 v27, 0xffff0000, v135
	v_pk_add_f32 v[14:15], v[14:15], v[22:23]
	v_pk_add_f32 v[12:13], v[12:13], v[20:21]
	v_pk_add_f32 v[20:21], v[10:11], v[26:27]
	v_pk_add_f32 v[10:11], v[8:9], v[24:25]
	v_mul_f32_e32 v8, v13, v13
	v_mul_f32_e32 v9, v15, v15
	v_fmac_f32_e32 v8, v12, v12
	v_fmac_f32_e32 v9, v14, v14
	v_add_f32_e32 v8, v8, v9
	v_mul_f32_e32 v9, v11, v11
	v_mul_f32_e32 v22, v21, v21
	v_fmac_f32_e32 v9, v10, v10
	v_fmac_f32_e32 v22, v20, v20
	v_add_f32_e32 v9, v9, v22
	v_add_f32_e32 v24, v8, v9
	v_cvt_pk_bf16_f32 v8, v12, v13
	v_cvt_pk_bf16_f32 v9, v14, v15
	v_lshlrev_b32_e32 v12, 16, v120
	v_and_b32_e32 v13, 0xffff0000, v120
	v_lshlrev_b32_e32 v14, 16, v121
	v_and_b32_e32 v15, 0xffff0000, v121
	v_cvt_pk_bf16_f32 v10, v10, v11
	v_cvt_pk_bf16_f32 v11, v20, v21
	v_lshlrev_b32_e32 v20, 16, v122
	v_and_b32_e32 v21, 0xffff0000, v122
	v_pk_add_f32 v[6:7], v[6:7], v[14:15]
	v_pk_add_f32 v[4:5], v[4:5], v[12:13]
	v_lshlrev_b32_e32 v22, 16, v123
	v_and_b32_e32 v23, 0xffff0000, v123
	v_pk_add_f32 v[14:15], v[0:1], v[20:21]
	v_mul_f32_e32 v0, v5, v5
	v_mul_f32_e32 v1, v7, v7
	v_pk_add_f32 v[12:13], v[2:3], v[22:23]
	v_fmac_f32_e32 v0, v4, v4
	v_fmac_f32_e32 v1, v6, v6
	v_add_f32_e32 v0, v0, v1
	v_mul_f32_e32 v1, v15, v15
	v_mul_f32_e32 v2, v13, v13
	v_fmac_f32_e32 v1, v14, v14
	v_fmac_f32_e32 v2, v12, v12
	v_add_f32_e32 v1, v1, v2
	v_add_f32_e32 v0, v0, v1
	v_add_f32_e32 v3, v24, v0
	ds_bpermute_b32 v20, v112, v3
	v_add_u32_e32 v16, 0xb0, v216
	s_waitcnt lgkmcnt(1)
	v_ashrrev_i32_e32 v17, 31, v16
	v_lshlrev_b64 v[18:19], 11, v[16:17]
	v_lshl_add_u64 v[0:1], s[10:11], 0, v[18:19]
	v_lshl_add_u64 v[18:19], v[214:215], 1, v[0:1]
	s_waitcnt lgkmcnt(0)
	v_add_f32_e32 v0, v3, v20
	ds_bpermute_b32 v1, v113, v0
	global_store_dwordx4 v[18:19], v[8:11], off
	v_cvt_pk_bf16_f32 v2, v4, v5
	v_cvt_pk_bf16_f32 v3, v6, v7
	v_cvt_pk_bf16_f32 v4, v14, v15
	v_cvt_pk_bf16_f32 v5, v12, v13
	global_store_dwordx4 v[18:19], v[2:5], off offset:256
	s_and_saveexec_b64 s[0:1], vcc
	s_cbranch_execz .LBB0_533
	v_lshlrev_b64 v[2:3], 6, v[16:17]
	v_lshl_add_u64 v[2:3], s[12:13], 0, v[2:3]
	v_lshl_add_u64 v[2:3], s[26:27], 2, v[2:3]
	s_lshl_b32 s72, s17, 2
	v_lshl_add_u64 v[2:3], v[2:3], 0, s[72:73]
	s_waitcnt lgkmcnt(0)
	v_add_f32_e32 v0, v0, v1
	global_store_dword v[2:3], v0, off

; __device__ __forceinline__ u32x4 pack8(const f32x4 v0, const f32x4 v1) { u32x4 w; w.x = cvt_pk_bf16(v0[0], v0[1]); w.y = cvt_pk_bf16(v0[2], v0[3]); w.z = cvt_pk_bf16(v1[0], v1[1]); w.w = cvt_pk_bf16(v1[2], v1[3]); return w; }
; __device__ __forceinline__ float sumsq8(const f32x4 a, const f32x4 b) { return ((a[0] * a[0] + a[1] * a[1]) + (a[2] * a[2] + a[3] * a[3])) + ((b[0] * b[0] + b[1] * b[1]) + (b[2] * b[2] + b[3] * b[3])); }
; __device__ __forceinline__ void unpack8(const u32x4 w, f32x4& a, f32x4& b) { a = (f32x4){bf_lo(w.x), bf_hi(w.x), bf_lo(w.y), bf_hi(w.y)}; b = (f32x4){bf_lo(w.z), bf_hi(w.z), bf_lo(w.w), bf_hi(w.w)}; }
;     __device__ __forceinline__ void operator()(const f32x4 (&acc)[2][2][4][2], const Unit& u, int wr, int wc, int fr, int fq) const {
;         const int row0 = u.pm * BM + wr * 64 + fr, col0 = u.pn * BM + wc * 32 + 8 * fq;
;         u32x4 rv[8][2];
; #pragma unroll
;         for (int i = 0; i < 8; ++i)
; #pragma unroll
;             for (int bj = 0; bj < 2; ++bj) rv[i][bj] = *(const u32x4*)(Rin + (size_t)(row0 + (i >> 2) * HALF + (i & 3) * 16) * DMODEL + col0 + bj * HALF);
; #pragma unroll
;         for (int ai = 0; ai < 2; ++ai)
; #pragma unroll
;             for (int m = 0; m < 4; ++m) { const int row = row0 + ai * HALF + m * 16; float part = 0.f;
; #pragma unroll
;                 for (int bj = 0; bj < 2; ++bj) { f32x4 r0, r1; unpack8(rv[ai * 4 + m][bj], r0, r1);
;                     const f32x4 h0 = r0 + acc[ai][bj][m][0], h1 = r1 + acc[ai][bj][m][1]; part += sumsq8(h0, h1);
;                     *(u32x4*)(XBo + (size_t)row * DMODEL + col0 + bj * HALF) = pack8(h0, h1); }
;                 part += __shfl_xor(part, 16); part += __shfl_xor(part, 32);
;                 if (fq == 0) ssq[(size_t)row * 16 + u.pn * 4 + wc] = part; }
.LBB0_968:
	v_mov_b32_e32 v116, v192
	s_lshl_b32 s1, s24, 8
	v_readfirstlane_b32 s0, v116
	s_bfe_u32 s13, s0, 0x20006
	s_ashr_i32 s0, s0, 2
	s_andn2_b32 s0, s0, 63
	s_add_i32 s0, s0, s1
	v_and_or_b32 v216, v116, 15, s0
	s_lshl_b32 s0, s22, 8
	s_lshl_b32 s1, s13, 5
	v_bfe_u32 v249, v116, 4, 2
	s_or_b32 s0, s1, s0
	v_lshl_or_b32 v214, v249, 3, s0
	v_ashrrev_i32_e32 v215, 31, v214
	v_lshlrev_b64 v[234:235], 1, v[214:215]
	v_ashrrev_i32_e32 v217, 31, v216
	v_lshl_add_u64 v[120:121], s[6:7], 0, v[234:235]
	v_lshlrev_b64 v[236:237], 11, v[216:217]
	v_lshl_add_u64 v[116:117], v[120:121], 0, v[236:237]
	global_load_dwordx4 v[188:191], v[116:117], off
	global_load_dwordx4 v[184:187], v[116:117], off offset:256
	v_or_b32_e32 v230, 16, v216
	v_ashrrev_i32_e32 v231, 31, v230
	v_or_b32_e32 v226, 32, v216
	v_lshlrev_b64 v[232:233], 11, v[230:231]
	v_ashrrev_i32_e32 v227, 31, v226
	v_or_b32_e32 v222, 48, v216
	v_lshl_add_u64 v[116:117], v[120:121], 0, v[232:233]
	v_lshlrev_b64 v[228:229], 11, v[226:227]
	v_ashrrev_i32_e32 v223, 31, v222
	v_add_u32_e32 v218, 0x80, v216
	global_load_dwordx4 v[180:183], v[116:117], off
	global_load_dwordx4 v[176:179], v[116:117], off offset:256
	v_lshl_add_u64 v[116:117], v[120:121], 0, v[228:229]
	v_lshlrev_b64 v[224:225], 11, v[222:223]
	v_ashrrev_i32_e32 v219, 31, v218
	global_load_dwordx4 v[172:175], v[116:117], off
	global_load_dwordx4 v[168:171], v[116:117], off offset:256
	v_lshl_add_u64 v[116:117], v[120:121], 0, v[224:225]
	v_lshlrev_b64 v[220:221], 11, v[218:219]
	global_load_dwordx4 v[164:167], v[116:117], off
	global_load_dwordx4 v[160:163], v[116:117], off offset:256
	v_lshl_add_u64 v[116:117], v[120:121], 0, v[220:221]
	global_load_dwordx4 v[156:159], v[116:117], off
	global_load_dwordx4 v[144:147], v[116:117], off offset:256
	v_add_u32_e32 v116, 0x90, v216
	v_ashrrev_i32_e32 v117, 31, v116
	v_lshlrev_b64 v[116:117], 11, v[116:117]
	v_lshl_add_u64 v[116:117], v[120:121], 0, v[116:117]
	global_load_dwordx4 v[140:143], v[116:117], off
	global_load_dwordx4 v[136:139], v[116:117], off offset:256
	v_add_u32_e32 v116, 0xa0, v216
	v_add_u32_e32 v122, 0xb0, v216
	v_ashrrev_i32_e32 v117, 31, v116
	v_ashrrev_i32_e32 v123, 31, v122
	v_lshlrev_b64 v[116:117], 11, v[116:117]
	v_lshlrev_b64 v[122:123], 11, v[122:123]
	v_lshl_add_u64 v[116:117], v[120:121], 0, v[116:117]
	v_lshl_add_u64 v[120:121], v[120:121], 0, v[122:123]
	global_load_dwordx4 v[128:131], v[116:117], off
	s_nop 0
	global_load_dwordx4 v[116:119], v[116:117], off offset:256
	s_nop 0
	global_load_dwordx4 v[132:135], v[120:121], off
	s_nop 0
	global_load_dwordx4 v[120:123], v[120:121], off offset:256
	s_lshl_b32 s22, s22, 2
	v_cmp_eq_u32_e32 vcc, 0, v249
	s_ashr_i32 s23, s22, 31
	s_waitcnt vmcnt(14)
	v_lshlrev_b32_e32 v250, 16, v188
	v_and_b32_e32 v251, 0xffff0000, v188
	v_lshlrev_b32_e32 v188, 16, v189
	v_and_b32_e32 v189, 0xffff0000, v189
	v_lshlrev_b32_e32 v252, 16, v190
	v_and_b32_e32 v253, 0xffff0000, v190
	v_lshlrev_b32_e32 v190, 16, v191
	v_and_b32_e32 v191, 0xffff0000, v191
	v_pk_add_f32 v[154:155], v[154:155], v[188:189]
	v_pk_add_f32 v[152:153], v[152:153], v[250:251]
	v_pk_add_f32 v[188:189], v[150:151], v[190:191]
	v_pk_add_f32 v[150:151], v[148:149], v[252:253]
	v_mul_f32_e32 v148, v153, v153
	v_mul_f32_e32 v149, v155, v155
	v_fmac_f32_e32 v148, v152, v152
	v_fmac_f32_e32 v149, v154, v154
	v_add_f32_e32 v148, v148, v149
	v_mul_f32_e32 v149, v151, v151
	v_mul_f32_e32 v190, v189, v189
	v_fmac_f32_e32 v149, v150, v150
	v_fmac_f32_e32 v190, v188, v188
	v_add_f32_e32 v149, v149, v190
	v_add_f32_e32 v190, v148, v149
	v_cvt_pk_bf16_f32 v148, v152, v153
	v_lshl_add_u64 v[152:153], s[6:7], 0, v[236:237]
	v_cvt_pk_bf16_f32 v149, v154, v155
	v_cvt_pk_bf16_f32 v150, v150, v151
	v_cvt_pk_bf16_f32 v151, v188, v189
	v_lshl_add_u64 v[152:153], v[152:153], 0, v[234:235]
	global_store_dwordx4 v[152:153], v[148:151], off
	v_lshlrev_b32_e32 v154, 16, v186
	v_and_b32_e32 v155, 0xffff0000, v186
	v_lshlrev_b32_e32 v148, 16, v184
	v_and_b32_e32 v149, 0xffff0000, v184
	v_lshlrev_b32_e32 v150, 16, v185
	v_and_b32_e32 v151, 0xffff0000, v185
	v_lshlrev_b32_e32 v184, 16, v187
	v_and_b32_e32 v185, 0xffff0000, v187
	v_pk_add_f32 v[126:127], v[126:127], v[150:151]
	v_pk_add_f32 v[124:125], v[124:125], v[148:149]
	v_pk_add_f32 v[148:149], v[114:115], v[184:185]
	v_pk_add_f32 v[114:115], v[112:113], v[154:155]
	v_mul_f32_e32 v112, v125, v125
	v_mul_f32_e32 v113, v127, v127
	v_fmac_f32_e32 v112, v124, v124
	v_fmac_f32_e32 v113, v126, v126
	v_add_f32_e32 v112, v112, v113
	v_mul_f32_e32 v113, v115, v115
	v_mul_f32_e32 v150, v149, v149
	v_fmac_f32_e32 v113, v114, v114
	v_fmac_f32_e32 v150, v148, v148
	v_add_f32_e32 v113, v113, v150
	v_add_f32_e32 v112, v112, v113
	v_add_f32_e32 v150, v190, v112
	v_cvt_pk_bf16_f32 v112, v124, v125
	v_cvt_pk_bf16_f32 v113, v126, v127
	v_cvt_pk_bf16_f32 v114, v114, v115
	v_cvt_pk_bf16_f32 v115, v148, v149
	global_store_dwordx4 v[152:153], v[112:115], off offset:256
	s_nop 1
	v_and_b32_e32 v113, 64, v241
	v_xor_b32_e32 v112, 16, v241
	v_add_u32_e32 v113, 64, v113
	v_cmp_lt_i32_e64 s[0:1], v112, v113
	v_xor_b32_e32 v115, 32, v241
	s_nop 0
	v_cndmask_b32_e64 v112, v241, v112, s[0:1]
	v_lshlrev_b32_e32 v112, 2, v112
	ds_bpermute_b32 v114, v112, v150
	v_cmp_lt_i32_e64 s[0:1], v115, v113
	s_waitcnt lgkmcnt(0)
	v_add_f32_e32 v114, v150, v114
	v_cndmask_b32_e64 v113, v241, v115, s[0:1]
	v_lshlrev_b32_e32 v113, 2, v113
	ds_bpermute_b32 v115, v113, v114
	s_and_saveexec_b64 s[0:1], vcc
	s_cbranch_execz .LBB0_970
	v_lshlrev_b64 v[124:125], 6, v[216:217]
	v_lshl_add_u64 v[124:125], s[8:9], 0, v[124:125]
	v_lshl_add_u64 v[124:125], s[22:23], 2, v[124:125]
	s_lshl_b32 s72, s13, 2
	v_lshl_add_u64 v[124:125], v[124:125], 0, s[72:73]
	s_waitcnt lgkmcnt(0)
	v_add_f32_e32 v114, v114, v115
	global_store_dword v[124:125], v114, off
; __device__ __forceinline__ u32x4 pack8(const f32x4 v0, const f32x4 v1) { u32x4 w; w.x = cvt_pk_bf16(v0[0], v0[1]); w.y = cvt_pk_bf16(v0[2], v0[3]); w.z = cvt_pk_bf16(v1[0], v1[1]); w.w = cvt_pk_bf16(v1[2], v1[3]); return w; }
; __device__ __forceinline__ float sumsq8(const f32x4 a, const f32x4 b) { return ((a[0] * a[0] + a[1] * a[1]) + (a[2] * a[2] + a[3] * a[3])) + ((b[0] * b[0] + b[1] * b[1]) + (b[2] * b[2] + b[3] * b[3])); }
; __device__ __forceinline__ void unpack8(const u32x4 w, f32x4& a, f32x4& b) { a = (f32x4){bf_lo(w.x), bf_hi(w.x), bf_lo(w.y), bf_hi(w.y)}; b = (f32x4){bf_lo(w.z), bf_hi(w.z), bf_lo(w.w), bf_hi(w.w)}; }
;     __device__ __forceinline__ void operator()(const f32x4 (&acc)[2][2][4][2], const Unit& u, int wr, int wc, int fr, int fq) const {
;     ...
;         for (int ai = 0; ai < 2; ++ai)
; #pragma unroll
;             for (int m = 0; m < 4; ++m) { const int row = row0 + ai * HALF + m * 16; float part = 0.f;
; #pragma unroll
;                 for (int bj = 0; bj < 2; ++bj) { f32x4 r0, r1; unpack8(rv[ai * 4 + m][bj], r0, r1);
;                     const f32x4 h0 = r0 + acc[ai][bj][m][0], h1 = r1 + acc[ai][bj][m][1]; part += sumsq8(h0, h1);
;                     *(u32x4*)(XBo + (size_t)row * DMODEL + col0 + bj * HALF) = pack8(h0, h1); }
;                 part += __shfl_xor(part, 16); part += __shfl_xor(part, 32);
;                 if (fq == 0) ssq[(size_t)row * 16 + u.pn * 4 + wc] = part; }
.LBB0_970:
	s_or_b64 exec, exec, s[0:1]
	s_waitcnt vmcnt(15)
	v_lshlrev_b32_e32 v114, 16, v180
	s_waitcnt lgkmcnt(0)
	v_and_b32_e32 v115, 0xffff0000, v180
	v_lshlrev_b32_e32 v124, 16, v181
	v_and_b32_e32 v125, 0xffff0000, v181
	v_lshlrev_b32_e32 v126, 16, v182
	v_and_b32_e32 v127, 0xffff0000, v182
	v_lshlrev_b32_e32 v148, 16, v183
	v_and_b32_e32 v149, 0xffff0000, v183
	v_pk_add_f32 v[110:111], v[110:111], v[124:125]
	v_pk_add_f32 v[108:109], v[108:109], v[114:115]
	v_pk_add_f32 v[114:115], v[106:107], v[148:149]
	v_pk_add_f32 v[106:107], v[104:105], v[126:127]
	v_mul_f32_e32 v104, v109, v109
	v_mul_f32_e32 v105, v111, v111
	v_fmac_f32_e32 v104, v108, v108
	v_fmac_f32_e32 v105, v110, v110
	v_add_f32_e32 v104, v104, v105
	v_mul_f32_e32 v105, v107, v107
	v_mul_f32_e32 v124, v115, v115
	v_fmac_f32_e32 v105, v106, v106
	v_fmac_f32_e32 v124, v114, v114
	v_add_f32_e32 v105, v105, v124
	v_add_f32_e32 v126, v104, v105
	v_cvt_pk_bf16_f32 v104, v108, v109
	v_cvt_pk_bf16_f32 v105, v110, v111
	v_lshlrev_b32_e32 v108, 16, v176
	v_and_b32_e32 v109, 0xffff0000, v176
	v_lshlrev_b32_e32 v110, 16, v177
	v_and_b32_e32 v111, 0xffff0000, v177
	v_cvt_pk_bf16_f32 v106, v106, v107
	v_cvt_pk_bf16_f32 v107, v114, v115
	v_lshlrev_b32_e32 v114, 16, v178
	v_and_b32_e32 v115, 0xffff0000, v178
	v_pk_add_f32 v[102:103], v[102:103], v[110:111]
	v_pk_add_f32 v[100:101], v[100:101], v[108:109]
	v_lshlrev_b32_e32 v124, 16, v179
	v_and_b32_e32 v125, 0xffff0000, v179
	v_pk_add_f32 v[110:111], v[96:97], v[114:115]
	v_mul_f32_e32 v96, v101, v101
	v_mul_f32_e32 v97, v103, v103
	v_pk_add_f32 v[108:109], v[98:99], v[124:125]
	v_fmac_f32_e32 v96, v100, v100
	v_fmac_f32_e32 v97, v102, v102
	v_add_f32_e32 v96, v96, v97
	v_mul_f32_e32 v97, v111, v111
	v_mul_f32_e32 v98, v109, v109
	v_fmac_f32_e32 v97, v110, v110
	v_fmac_f32_e32 v98, v108, v108
	v_add_f32_e32 v97, v97, v98
	v_add_f32_e32 v96, v96, v97
	v_add_f32_e32 v99, v126, v96
	ds_bpermute_b32 v124, v112, v99
	v_lshl_add_u64 v[96:97], s[6:7], 0, v[232:233]
	v_lshl_add_u64 v[114:115], v[214:215], 1, v[96:97]
	global_store_dwordx4 v[114:115], v[104:107], off
	v_cvt_pk_bf16_f32 v98, v100, v101
	s_waitcnt lgkmcnt(0)
	v_add_f32_e32 v96, v99, v124
	ds_bpermute_b32 v97, v113, v96
	v_cvt_pk_bf16_f32 v99, v102, v103
	v_cvt_pk_bf16_f32 v100, v110, v111
	v_cvt_pk_bf16_f32 v101, v108, v109
	global_store_dwordx4 v[114:115], v[98:101], off offset:256
	s_and_saveexec_b64 s[0:1], vcc
	s_cbranch_execz .LBB0_972
	v_lshlrev_b64 v[98:99], 6, v[230:231]
	v_lshl_add_u64 v[98:99], s[8:9], 0, v[98:99]
	v_lshl_add_u64 v[98:99], s[22:23], 2, v[98:99]
	s_lshl_b32 s72, s13, 2
	v_lshl_add_u64 v[98:99], v[98:99], 0, s[72:73]
	s_waitcnt lgkmcnt(0)
	v_add_f32_e32 v96, v96, v97
	global_store_dword v[98:99], v96, off
.LBB0_972:
	s_or_b64 exec, exec, s[0:1]
	s_waitcnt vmcnt(16)
	v_lshlrev_b32_e32 v96, 16, v172
	s_waitcnt lgkmcnt(0)
	v_and_b32_e32 v97, 0xffff0000, v172
	v_lshlrev_b32_e32 v98, 16, v173
	v_and_b32_e32 v99, 0xffff0000, v173
	v_lshlrev_b32_e32 v100, 16, v174
	v_and_b32_e32 v101, 0xffff0000, v174
	v_lshlrev_b32_e32 v102, 16, v175
	v_and_b32_e32 v103, 0xffff0000, v175
	v_pk_add_f32 v[94:95], v[94:95], v[98:99]
	v_pk_add_f32 v[92:93], v[92:93], v[96:97]
	v_pk_add_f32 v[96:97], v[90:91], v[102:103]
	v_pk_add_f32 v[90:91], v[88:89], v[100:101]
	v_mul_f32_e32 v88, v93, v93
	v_mul_f32_e32 v89, v95, v95
	v_fmac_f32_e32 v88, v92, v92
	v_fmac_f32_e32 v89, v94, v94
	v_add_f32_e32 v88, v88, v89
	v_mul_f32_e32 v89, v91, v91
	v_mul_f32_e32 v98, v97, v97
	v_fmac_f32_e32 v89, v90, v90
	v_fmac_f32_e32 v98, v96, v96
	v_add_f32_e32 v89, v89, v98
	v_add_f32_e32 v100, v88, v89
	v_cvt_pk_bf16_f32 v88, v92, v93
	v_cvt_pk_bf16_f32 v89, v94, v95
	v_lshlrev_b32_e32 v92, 16, v168
	v_and_b32_e32 v93, 0xffff0000, v168
	v_lshlrev_b32_e32 v94, 16, v169
	v_and_b32_e32 v95, 0xffff0000, v169
	v_cvt_pk_bf16_f32 v90, v90, v91
	v_cvt_pk_bf16_f32 v91, v96, v97
	v_lshlrev_b32_e32 v96, 16, v170
	v_and_b32_e32 v97, 0xffff0000, v170
	v_pk_add_f32 v[86:87], v[86:87], v[94:95]
	v_pk_add_f32 v[84:85], v[84:85], v[92:93]
	v_lshlrev_b32_e32 v98, 16, v171
	v_and_b32_e32 v99, 0xffff0000, v171
	v_pk_add_f32 v[94:95], v[80:81], v[96:97]
	v_mul_f32_e32 v80, v85, v85
	v_mul_f32_e32 v81, v87, v87
	v_pk_add_f32 v[92:93], v[82:83], v[98:99]
	v_fmac_f32_e32 v80, v84, v84
	v_fmac_f32_e32 v81, v86, v86
	v_add_f32_e32 v80, v80, v81
	v_mul_f32_e32 v81, v95, v95
	v_mul_f32_e32 v82, v93, v93
	v_fmac_f32_e32 v81, v94, v94
	v_fmac_f32_e32 v82, v92, v92
	v_add_f32_e32 v81, v81, v82
	v_add_f32_e32 v80, v80, v81
	v_add_f32_e32 v83, v100, v80
	ds_bpermute_b32 v98, v112, v83
	v_lshl_add_u64 v[80:81], s[6:7], 0, v[228:229]
	v_lshl_add_u64 v[96:97], v[214:215], 1, v[80:81]
	global_store_dwordx4 v[96:97], v[88:91], off
	v_cvt_pk_bf16_f32 v82, v84, v85
	s_waitcnt lgkmcnt(0)
	v_add_f32_e32 v80, v83, v98
	ds_bpermute_b32 v81, v113, v80
	v_cvt_pk_bf16_f32 v83, v86, v87
	v_cvt_pk_bf16_f32 v84, v94, v95
	v_cvt_pk_bf16_f32 v85, v92, v93
	global_store_dwordx4 v[96:97], v[82:85], off offset:256
	s_and_saveexec_b64 s[0:1], vcc
	s_cbranch_execz .LBB0_974
	v_lshlrev_b64 v[82:83], 6, v[226:227]
	v_lshl_add_u64 v[82:83], s[8:9], 0, v[82:83]
	v_lshl_add_u64 v[82:83], s[22:23], 2, v[82:83]
	s_lshl_b32 s72, s13, 2
	v_lshl_add_u64 v[82:83], v[82:83], 0, s[72:73]
	s_waitcnt lgkmcnt(0)
	v_add_f32_e32 v80, v80, v81
	global_store_dword v[82:83], v80, off
; __device__ __forceinline__ u32x4 pack8(const f32x4 v0, const f32x4 v1) { u32x4 w; w.x = cvt_pk_bf16(v0[0], v0[1]); w.y = cvt_pk_bf16(v0[2], v0[3]); w.z = cvt_pk_bf16(v1[0], v1[1]); w.w = cvt_pk_bf16(v1[2], v1[3]); return w; }
; __device__ __forceinline__ float sumsq8(const f32x4 a, const f32x4 b) { return ((a[0] * a[0] + a[1] * a[1]) + (a[2] * a[2] + a[3] * a[3])) + ((b[0] * b[0] + b[1] * b[1]) + (b[2] * b[2] + b[3] * b[3])); }
; __device__ __forceinline__ void unpack8(const u32x4 w, f32x4& a, f32x4& b) { a = (f32x4){bf_lo(w.x), bf_hi(w.x), bf_lo(w.y), bf_hi(w.y)}; b = (f32x4){bf_lo(w.z), bf_hi(w.z), bf_lo(w.w), bf_hi(w.w)}; }
;     __device__ __forceinline__ void operator()(const f32x4 (&acc)[2][2][4][2], const Unit& u, int wr, int wc, int fr, int fq) const {
;     ...
;         for (int ai = 0; ai < 2; ++ai)
; #pragma unroll
;             for (int m = 0; m < 4; ++m) { const int row = row0 + ai * HALF + m * 16; float part = 0.f;
; #pragma unroll
;                 for (int bj = 0; bj < 2; ++bj) { f32x4 r0, r1; unpack8(rv[ai * 4 + m][bj], r0, r1);
;                     const f32x4 h0 = r0 + acc[ai][bj][m][0], h1 = r1 + acc[ai][bj][m][1]; part += sumsq8(h0, h1);
;                     *(u32x4*)(XBo + (size_t)row * DMODEL + col0 + bj * HALF) = pack8(h0, h1); }
;                 part += __shfl_xor(part, 16); part += __shfl_xor(part, 32);
;                 if (fq == 0) ssq[(size_t)row * 16 + u.pn * 4 + wc] = part; }
.LBB0_974:
	s_or_b64 exec, exec, s[0:1]
	s_waitcnt vmcnt(17)
	v_lshlrev_b32_e32 v80, 16, v164
	s_waitcnt lgkmcnt(0)
	v_and_b32_e32 v81, 0xffff0000, v164
	v_lshlrev_b32_e32 v82, 16, v165
	v_and_b32_e32 v83, 0xffff0000, v165
	v_lshlrev_b32_e32 v84, 16, v166
	v_and_b32_e32 v85, 0xffff0000, v166
	v_lshlrev_b32_e32 v86, 16, v167
	v_and_b32_e32 v87, 0xffff0000, v167
	v_pk_add_f32 v[78:79], v[78:79], v[82:83]
	v_pk_add_f32 v[76:77], v[76:77], v[80:81]
	v_pk_add_f32 v[80:81], v[74:75], v[86:87]
	v_pk_add_f32 v[74:75], v[72:73], v[84:85]
	v_mul_f32_e32 v72, v77, v77
	v_mul_f32_e32 v73, v79, v79
	v_fmac_f32_e32 v72, v76, v76
	v_fmac_f32_e32 v73, v78, v78
	v_add_f32_e32 v72, v72, v73
	v_mul_f32_e32 v73, v75, v75
	v_mul_f32_e32 v82, v81, v81
	v_fmac_f32_e32 v73, v74, v74
	v_fmac_f32_e32 v82, v80, v80
	v_add_f32_e32 v73, v73, v82
	v_add_f32_e32 v84, v72, v73
	v_cvt_pk_bf16_f32 v72, v76, v77
	v_cvt_pk_bf16_f32 v73, v78, v79
	v_lshlrev_b32_e32 v76, 16, v160
	v_and_b32_e32 v77, 0xffff0000, v160
	v_lshlrev_b32_e32 v78, 16, v161
	v_and_b32_e32 v79, 0xffff0000, v161
	v_cvt_pk_bf16_f32 v74, v74, v75
	v_cvt_pk_bf16_f32 v75, v80, v81
	v_lshlrev_b32_e32 v80, 16, v162
	v_and_b32_e32 v81, 0xffff0000, v162
	v_pk_add_f32 v[70:71], v[70:71], v[78:79]
	v_pk_add_f32 v[68:69], v[68:69], v[76:77]
	v_lshlrev_b32_e32 v82, 16, v163
	v_and_b32_e32 v83, 0xffff0000, v163
	v_pk_add_f32 v[78:79], v[64:65], v[80:81]
	v_mul_f32_e32 v64, v69, v69
	v_mul_f32_e32 v65, v71, v71
	v_pk_add_f32 v[76:77], v[66:67], v[82:83]
	v_fmac_f32_e32 v64, v68, v68
	v_fmac_f32_e32 v65, v70, v70
	v_add_f32_e32 v64, v64, v65
	v_mul_f32_e32 v65, v79, v79
	v_mul_f32_e32 v66, v77, v77
	v_fmac_f32_e32 v65, v78, v78
	v_fmac_f32_e32 v66, v76, v76
	v_add_f32_e32 v65, v65, v66
	v_add_f32_e32 v64, v64, v65
	v_add_f32_e32 v67, v84, v64
	ds_bpermute_b32 v82, v112, v67
	v_lshl_add_u64 v[64:65], s[6:7], 0, v[224:225]
	v_lshl_add_u64 v[80:81], v[214:215], 1, v[64:65]
	global_store_dwordx4 v[80:81], v[72:75], off
	v_cvt_pk_bf16_f32 v66, v68, v69
	s_waitcnt lgkmcnt(0)
	v_add_f32_e32 v64, v67, v82
	ds_bpermute_b32 v65, v113, v64
	v_cvt_pk_bf16_f32 v67, v70, v71
	v_cvt_pk_bf16_f32 v68, v78, v79
	v_cvt_pk_bf16_f32 v69, v76, v77
	global_store_dwordx4 v[80:81], v[66:69], off offset:256
	s_and_saveexec_b64 s[0:1], vcc
	s_cbranch_execz .LBB0_976
	v_lshlrev_b64 v[66:67], 6, v[222:223]
	v_lshl_add_u64 v[66:67], s[8:9], 0, v[66:67]
	v_lshl_add_u64 v[66:67], s[22:23], 2, v[66:67]
	s_lshl_b32 s72, s13, 2
	v_lshl_add_u64 v[66:67], v[66:67], 0, s[72:73]
	s_waitcnt lgkmcnt(0)
	v_add_f32_e32 v64, v64, v65
	global_store_dword v[66:67], v64, off
.LBB0_976:
	s_or_b64 exec, exec, s[0:1]
	s_waitcnt vmcnt(18)
	v_lshlrev_b32_e32 v64, 16, v156
	s_waitcnt lgkmcnt(0)
	v_and_b32_e32 v65, 0xffff0000, v156
	v_lshlrev_b32_e32 v66, 16, v157
	v_and_b32_e32 v67, 0xffff0000, v157
	v_lshlrev_b32_e32 v68, 16, v158
	v_and_b32_e32 v69, 0xffff0000, v158
	v_lshlrev_b32_e32 v70, 16, v159
	v_and_b32_e32 v71, 0xffff0000, v159
	v_pk_add_f32 v[62:63], v[62:63], v[66:67]
	v_pk_add_f32 v[60:61], v[60:61], v[64:65]
	v_pk_add_f32 v[64:65], v[58:59], v[70:71]
	v_pk_add_f32 v[58:59], v[56:57], v[68:69]
	v_mul_f32_e32 v56, v61, v61
	v_mul_f32_e32 v57, v63, v63
	v_fmac_f32_e32 v56, v60, v60
	v_fmac_f32_e32 v57, v62, v62
	v_add_f32_e32 v56, v56, v57
	v_mul_f32_e32 v57, v59, v59
	v_mul_f32_e32 v66, v65, v65
	v_fmac_f32_e32 v57, v58, v58
	v_fmac_f32_e32 v66, v64, v64
	v_add_f32_e32 v57, v57, v66
	v_add_f32_e32 v68, v56, v57
	v_cvt_pk_bf16_f32 v56, v60, v61
	v_cvt_pk_bf16_f32 v57, v62, v63
	v_lshlrev_b32_e32 v60, 16, v144
	v_and_b32_e32 v61, 0xffff0000, v144
	v_lshlrev_b32_e32 v62, 16, v145
	v_and_b32_e32 v63, 0xffff0000, v145
	v_cvt_pk_bf16_f32 v58, v58, v59
	v_cvt_pk_bf16_f32 v59, v64, v65
	v_lshlrev_b32_e32 v64, 16, v146
	v_and_b32_e32 v65, 0xffff0000, v146
	v_pk_add_f32 v[54:55], v[54:55], v[62:63]
	v_pk_add_f32 v[52:53], v[52:53], v[60:61]
	v_lshlrev_b32_e32 v66, 16, v147
	v_and_b32_e32 v67, 0xffff0000, v147
	v_pk_add_f32 v[62:63], v[48:49], v[64:65]
	v_mul_f32_e32 v48, v53, v53
	v_mul_f32_e32 v49, v55, v55
	v_pk_add_f32 v[60:61], v[50:51], v[66:67]
	v_fmac_f32_e32 v48, v52, v52
	v_fmac_f32_e32 v49, v54, v54
	v_add_f32_e32 v48, v48, v49
	v_mul_f32_e32 v49, v63, v63
	v_mul_f32_e32 v50, v61, v61
	v_fmac_f32_e32 v49, v62, v62
	v_fmac_f32_e32 v50, v60, v60
	v_add_f32_e32 v49, v49, v50
	v_add_f32_e32 v48, v48, v49
	v_add_f32_e32 v51, v68, v48
	ds_bpermute_b32 v66, v112, v51
	v_lshl_add_u64 v[48:49], s[6:7], 0, v[220:221]
	v_lshl_add_u64 v[64:65], v[214:215], 1, v[48:49]
	global_store_dwordx4 v[64:65], v[56:59], off
	v_cvt_pk_bf16_f32 v50, v52, v53
	s_waitcnt lgkmcnt(0)
	v_add_f32_e32 v48, v51, v66
	ds_bpermute_b32 v49, v113, v48
	v_cvt_pk_bf16_f32 v51, v54, v55
	v_cvt_pk_bf16_f32 v52, v62, v63
	v_cvt_pk_bf16_f32 v53, v60, v61
	global_store_dwordx4 v[64:65], v[50:53], off offset:256
	s_and_saveexec_b64 s[0:1], vcc
	s_cbranch_execz .LBB0_978
	v_lshlrev_b64 v[50:51], 6, v[218:219]
	v_lshl_add_u64 v[50:51], s[8:9], 0, v[50:51]
	v_lshl_add_u64 v[50:51], s[22:23], 2, v[50:51]
	s_lshl_b32 s72, s13, 2
	v_lshl_add_u64 v[50:51], v[50:51], 0, s[72:73]
	s_waitcnt lgkmcnt(0)
	v_add_f32_e32 v48, v48, v49
	global_store_dword v[50:51], v48, off
; __device__ __forceinline__ u32x4 pack8(const f32x4 v0, const f32x4 v1) { u32x4 w; w.x = cvt_pk_bf16(v0[0], v0[1]); w.y = cvt_pk_bf16(v0[2], v0[3]); w.z = cvt_pk_bf16(v1[0], v1[1]); w.w = cvt_pk_bf16(v1[2], v1[3]); return w; }
; __device__ __forceinline__ float sumsq8(const f32x4 a, const f32x4 b) { return ((a[0] * a[0] + a[1] * a[1]) + (a[2] * a[2] + a[3] * a[3])) + ((b[0] * b[0] + b[1] * b[1]) + (b[2] * b[2] + b[3] * b[3])); }
; __device__ __forceinline__ void unpack8(const u32x4 w, f32x4& a, f32x4& b) { a = (f32x4){bf_lo(w.x), bf_hi(w.x), bf_lo(w.y), bf_hi(w.y)}; b = (f32x4){bf_lo(w.z), bf_hi(w.z), bf_lo(w.w), bf_hi(w.w)}; }
;     __device__ __forceinline__ void operator()(const f32x4 (&acc)[2][2][4][2], const Unit& u, int wr, int wc, int fr, int fq) const {
;     ...
;         for (int ai = 0; ai < 2; ++ai)
; #pragma unroll
;             for (int m = 0; m < 4; ++m) { const int row = row0 + ai * HALF + m * 16; float part = 0.f;
; #pragma unroll
;                 for (int bj = 0; bj < 2; ++bj) { f32x4 r0, r1; unpack8(rv[ai * 4 + m][bj], r0, r1);
;                     const f32x4 h0 = r0 + acc[ai][bj][m][0], h1 = r1 + acc[ai][bj][m][1]; part += sumsq8(h0, h1);
;                     *(u32x4*)(XBo + (size_t)row * DMODEL + col0 + bj * HALF) = pack8(h0, h1); }
;                 part += __shfl_xor(part, 16); part += __shfl_xor(part, 32);
;                 if (fq == 0) ssq[(size_t)row * 16 + u.pn * 4 + wc] = part; }
.LBB0_978:
	s_or_b64 exec, exec, s[0:1]
	s_waitcnt vmcnt(19)
	v_lshlrev_b32_e32 v52, 16, v140
	v_and_b32_e32 v53, 0xffff0000, v140
	v_lshlrev_b32_e32 v54, 16, v141
	v_and_b32_e32 v55, 0xffff0000, v141
	v_lshlrev_b32_e32 v56, 16, v142
	v_and_b32_e32 v57, 0xffff0000, v142
	v_lshlrev_b32_e32 v58, 16, v143
	v_and_b32_e32 v59, 0xffff0000, v143
	v_pk_add_f32 v[46:47], v[46:47], v[54:55]
	v_pk_add_f32 v[44:45], v[44:45], v[52:53]
	v_pk_add_f32 v[52:53], v[42:43], v[58:59]
	v_pk_add_f32 v[42:43], v[40:41], v[56:57]
	v_mul_f32_e32 v40, v45, v45
	v_mul_f32_e32 v41, v47, v47
	v_fmac_f32_e32 v40, v44, v44
	v_fmac_f32_e32 v41, v46, v46
	v_add_f32_e32 v40, v40, v41
	v_mul_f32_e32 v41, v43, v43
	v_mul_f32_e32 v54, v53, v53
	v_fmac_f32_e32 v41, v42, v42
	v_fmac_f32_e32 v54, v52, v52
	v_add_f32_e32 v41, v41, v54
	v_add_f32_e32 v56, v40, v41
	v_cvt_pk_bf16_f32 v40, v44, v45
	v_cvt_pk_bf16_f32 v41, v46, v47
	v_lshlrev_b32_e32 v44, 16, v136
	v_and_b32_e32 v45, 0xffff0000, v136
	v_lshlrev_b32_e32 v46, 16, v137
	v_and_b32_e32 v47, 0xffff0000, v137
	v_cvt_pk_bf16_f32 v42, v42, v43
	v_cvt_pk_bf16_f32 v43, v52, v53
	v_lshlrev_b32_e32 v52, 16, v138
	v_and_b32_e32 v53, 0xffff0000, v138
	v_pk_add_f32 v[38:39], v[38:39], v[46:47]
	v_pk_add_f32 v[36:37], v[36:37], v[44:45]
	v_lshlrev_b32_e32 v54, 16, v139
	v_and_b32_e32 v55, 0xffff0000, v139
	v_pk_add_f32 v[46:47], v[32:33], v[52:53]
	v_mul_f32_e32 v32, v37, v37
	v_mul_f32_e32 v33, v39, v39
	v_pk_add_f32 v[44:45], v[34:35], v[54:55]
	v_fmac_f32_e32 v32, v36, v36
	v_fmac_f32_e32 v33, v38, v38
	v_add_f32_e32 v32, v32, v33
	v_mul_f32_e32 v33, v47, v47
	v_mul_f32_e32 v34, v45, v45
	v_fmac_f32_e32 v33, v46, v46
	v_fmac_f32_e32 v34, v44, v44
	v_add_f32_e32 v33, v33, v34
	v_add_f32_e32 v32, v32, v33
	v_add_f32_e32 v35, v56, v32
	ds_bpermute_b32 v52, v112, v35
	v_add_u32_e32 v48, 0x90, v216
	s_waitcnt lgkmcnt(1)
	v_ashrrev_i32_e32 v49, 31, v48
	v_lshlrev_b64 v[50:51], 11, v[48:49]
	v_lshl_add_u64 v[32:33], s[6:7], 0, v[50:51]
	v_lshl_add_u64 v[50:51], v[214:215], 1, v[32:33]
	s_waitcnt lgkmcnt(0)
	v_add_f32_e32 v32, v35, v52
	ds_bpermute_b32 v33, v113, v32
	global_store_dwordx4 v[50:51], v[40:43], off
	v_cvt_pk_bf16_f32 v34, v36, v37
	v_cvt_pk_bf16_f32 v35, v38, v39
	v_cvt_pk_bf16_f32 v36, v46, v47
	v_cvt_pk_bf16_f32 v37, v44, v45
	global_store_dwordx4 v[50:51], v[34:37], off offset:256
	s_and_saveexec_b64 s[0:1], vcc
	s_cbranch_execz .LBB0_980
	v_lshlrev_b64 v[34:35], 6, v[48:49]
	v_lshl_add_u64 v[34:35], s[8:9], 0, v[34:35]
	v_lshl_add_u64 v[34:35], s[22:23], 2, v[34:35]
	s_lshl_b32 s72, s13, 2
	v_lshl_add_u64 v[34:35], v[34:35], 0, s[72:73]
	s_waitcnt lgkmcnt(0)
	v_add_f32_e32 v32, v32, v33
	global_store_dword v[34:35], v32, off
; __device__ __forceinline__ u32x4 pack8(const f32x4 v0, const f32x4 v1) { u32x4 w; w.x = cvt_pk_bf16(v0[0], v0[1]); w.y = cvt_pk_bf16(v0[2], v0[3]); w.z = cvt_pk_bf16(v1[0], v1[1]); w.w = cvt_pk_bf16(v1[2], v1[3]); return w; }
; __device__ __forceinline__ float sumsq8(const f32x4 a, const f32x4 b) { return ((a[0] * a[0] + a[1] * a[1]) + (a[2] * a[2] + a[3] * a[3])) + ((b[0] * b[0] + b[1] * b[1]) + (b[2] * b[2] + b[3] * b[3])); }
; __device__ __forceinline__ void unpack8(const u32x4 w, f32x4& a, f32x4& b) { a = (f32x4){bf_lo(w.x), bf_hi(w.x), bf_lo(w.y), bf_hi(w.y)}; b = (f32x4){bf_lo(w.z), bf_hi(w.z), bf_lo(w.w), bf_hi(w.w)}; }
;     __device__ __forceinline__ void operator()(const f32x4 (&acc)[2][2][4][2], const Unit& u, int wr, int wc, int fr, int fq) const {
;     ...
;         for (int ai = 0; ai < 2; ++ai)
; #pragma unroll
;             for (int m = 0; m < 4; ++m) { const int row = row0 + ai * HALF + m * 16; float part = 0.f;
; #pragma unroll
;                 for (int bj = 0; bj < 2; ++bj) { f32x4 r0, r1; unpack8(rv[ai * 4 + m][bj], r0, r1);
;                     const f32x4 h0 = r0 + acc[ai][bj][m][0], h1 = r1 + acc[ai][bj][m][1]; part += sumsq8(h0, h1);
;                     *(u32x4*)(XBo + (size_t)row * DMODEL + col0 + bj * HALF) = pack8(h0, h1); }
;                 part += __shfl_xor(part, 16); part += __shfl_xor(part, 32);
;                 if (fq == 0) ssq[(size_t)row * 16 + u.pn * 4 + wc] = part; }
.LBB0_980:
	s_or_b64 exec, exec, s[0:1]
	s_waitcnt vmcnt(20)
	v_lshlrev_b32_e32 v36, 16, v128
	v_and_b32_e32 v37, 0xffff0000, v128
	v_lshlrev_b32_e32 v38, 16, v129
	v_and_b32_e32 v39, 0xffff0000, v129
	v_lshlrev_b32_e32 v40, 16, v130
	v_and_b32_e32 v41, 0xffff0000, v130
	v_lshlrev_b32_e32 v42, 16, v131
	v_and_b32_e32 v43, 0xffff0000, v131
	v_pk_add_f32 v[30:31], v[30:31], v[38:39]
	v_pk_add_f32 v[28:29], v[28:29], v[36:37]
	v_pk_add_f32 v[36:37], v[26:27], v[42:43]
	v_pk_add_f32 v[26:27], v[24:25], v[40:41]
	v_mul_f32_e32 v24, v29, v29
	v_mul_f32_e32 v25, v31, v31
	v_fmac_f32_e32 v24, v28, v28
	v_fmac_f32_e32 v25, v30, v30
	v_add_f32_e32 v24, v24, v25
	v_mul_f32_e32 v25, v27, v27
	v_mul_f32_e32 v38, v37, v37
	v_fmac_f32_e32 v25, v26, v26
	v_fmac_f32_e32 v38, v36, v36
	v_add_f32_e32 v25, v25, v38
	v_add_f32_e32 v40, v24, v25
	v_cvt_pk_bf16_f32 v24, v28, v29
	v_cvt_pk_bf16_f32 v25, v30, v31
	v_lshlrev_b32_e32 v28, 16, v116
	v_and_b32_e32 v29, 0xffff0000, v116
	v_lshlrev_b32_e32 v30, 16, v117
	v_and_b32_e32 v31, 0xffff0000, v117
	v_cvt_pk_bf16_f32 v26, v26, v27
	v_cvt_pk_bf16_f32 v27, v36, v37
	v_lshlrev_b32_e32 v36, 16, v118
	v_and_b32_e32 v37, 0xffff0000, v118
	v_pk_add_f32 v[22:23], v[22:23], v[30:31]
	v_pk_add_f32 v[20:21], v[20:21], v[28:29]
	v_lshlrev_b32_e32 v38, 16, v119
	v_and_b32_e32 v39, 0xffff0000, v119
	v_pk_add_f32 v[30:31], v[16:17], v[36:37]
	v_mul_f32_e32 v16, v21, v21
	v_mul_f32_e32 v17, v23, v23
	v_pk_add_f32 v[28:29], v[18:19], v[38:39]
	v_fmac_f32_e32 v16, v20, v20
	v_fmac_f32_e32 v17, v22, v22
	v_add_f32_e32 v16, v16, v17
	v_mul_f32_e32 v17, v31, v31
	v_mul_f32_e32 v18, v29, v29
	v_fmac_f32_e32 v17, v30, v30
	v_fmac_f32_e32 v18, v28, v28
	v_add_f32_e32 v17, v17, v18
	v_add_f32_e32 v16, v16, v17
	v_add_f32_e32 v19, v40, v16
	ds_bpermute_b32 v36, v112, v19
	v_add_u32_e32 v32, 0xa0, v216
	s_waitcnt lgkmcnt(1)
	v_ashrrev_i32_e32 v33, 31, v32
	v_lshlrev_b64 v[34:35], 11, v[32:33]
	v_lshl_add_u64 v[16:17], s[6:7], 0, v[34:35]
	v_lshl_add_u64 v[34:35], v[214:215], 1, v[16:17]
	s_waitcnt lgkmcnt(0)
	v_add_f32_e32 v16, v19, v36
	ds_bpermute_b32 v17, v113, v16
	global_store_dwordx4 v[34:35], v[24:27], off
	v_cvt_pk_bf16_f32 v18, v20, v21
	v_cvt_pk_bf16_f32 v19, v22, v23
	v_cvt_pk_bf16_f32 v20, v30, v31
	v_cvt_pk_bf16_f32 v21, v28, v29
	global_store_dwordx4 v[34:35], v[18:21], off offset:256
	s_and_saveexec_b64 s[0:1], vcc
	s_cbranch_execz .LBB0_982
	v_lshlrev_b64 v[18:19], 6, v[32:33]
	v_lshl_add_u64 v[18:19], s[8:9], 0, v[18:19]
	v_lshl_add_u64 v[18:19], s[22:23], 2, v[18:19]
	s_lshl_b32 s72, s13, 2
	v_lshl_add_u64 v[18:19], v[18:19], 0, s[72:73]
	s_waitcnt lgkmcnt(0)
	v_add_f32_e32 v16, v16, v17
	global_store_dword v[18:19], v16, off
.LBB0_982:
	s_or_b64 exec, exec, s[0:1]
	s_waitcnt vmcnt(21)
	v_lshlrev_b32_e32 v20, 16, v132
	v_and_b32_e32 v21, 0xffff0000, v132
	v_lshlrev_b32_e32 v22, 16, v133
	v_and_b32_e32 v23, 0xffff0000, v133
	v_lshlrev_b32_e32 v24, 16, v134
	v_and_b32_e32 v25, 0xffff0000, v134
	v_lshlrev_b32_e32 v26, 16, v135
	v_and_b32_e32 v27, 0xffff0000, v135
	v_pk_add_f32 v[14:15], v[14:15], v[22:23]
	v_pk_add_f32 v[12:13], v[12:13], v[20:21]
	v_pk_add_f32 v[20:21], v[10:11], v[26:27]
	v_pk_add_f32 v[10:11], v[8:9], v[24:25]
	v_mul_f32_e32 v8, v13, v13
	v_mul_f32_e32 v9, v15, v15
	v_fmac_f32_e32 v8, v12, v12
	v_fmac_f32_e32 v9, v14, v14
	v_add_f32_e32 v8, v8, v9
	v_mul_f32_e32 v9, v11, v11
	v_mul_f32_e32 v22, v21, v21
	v_fmac_f32_e32 v9, v10, v10
	v_fmac_f32_e32 v22, v20, v20
	v_add_f32_e32 v9, v9, v22
	v_add_f32_e32 v24, v8, v9
	v_cvt_pk_bf16_f32 v8, v12, v13
	v_cvt_pk_bf16_f32 v9, v14, v15
	v_lshlrev_b32_e32 v12, 16, v120
	v_and_b32_e32 v13, 0xffff0000, v120
	v_lshlrev_b32_e32 v14, 16, v121
	v_and_b32_e32 v15, 0xffff0000, v121
	v_cvt_pk_bf16_f32 v10, v10, v11
	v_cvt_pk_bf16_f32 v11, v20, v21
	v_lshlrev_b32_e32 v20, 16, v122
	v_and_b32_e32 v21, 0xffff0000, v122
	v_pk_add_f32 v[6:7], v[6:7], v[14:15]
	v_pk_add_f32 v[4:5], v[4:5], v[12:13]
	v_lshlrev_b32_e32 v22, 16, v123
	v_and_b32_e32 v23, 0xffff0000, v123
	v_pk_add_f32 v[14:15], v[0:1], v[20:21]
	v_mul_f32_e32 v0, v5, v5
	v_mul_f32_e32 v1, v7, v7
	v_pk_add_f32 v[12:13], v[2:3], v[22:23]
	v_fmac_f32_e32 v0, v4, v4
	v_fmac_f32_e32 v1, v6, v6
	v_add_f32_e32 v0, v0, v1
	v_mul_f32_e32 v1, v15, v15
	v_mul_f32_e32 v2, v13, v13
	v_fmac_f32_e32 v1, v14, v14
	v_fmac_f32_e32 v2, v12, v12
	v_add_f32_e32 v1, v1, v2
	v_add_f32_e32 v0, v0, v1
	v_add_f32_e32 v3, v24, v0
	ds_bpermute_b32 v20, v112, v3
	v_add_u32_e32 v16, 0xb0, v216
	s_waitcnt lgkmcnt(1)
	v_ashrrev_i32_e32 v17, 31, v16
	v_lshlrev_b64 v[18:19], 11, v[16:17]
	v_lshl_add_u64 v[0:1], s[6:7], 0, v[18:19]
	v_lshl_add_u64 v[18:19], v[214:215], 1, v[0:1]
	s_waitcnt lgkmcnt(0)
	v_add_f32_e32 v0, v3, v20
	ds_bpermute_b32 v1, v113, v0
	global_store_dwordx4 v[18:19], v[8:11], off
	v_cvt_pk_bf16_f32 v2, v4, v5
	v_cvt_pk_bf16_f32 v3, v6, v7
	v_cvt_pk_bf16_f32 v4, v14, v15
	v_cvt_pk_bf16_f32 v5, v12, v13
	global_store_dwordx4 v[18:19], v[2:5], off offset:256
	s_and_saveexec_b64 s[0:1], vcc
	s_cbranch_execz .LBB0_984
	v_lshlrev_b64 v[2:3], 6, v[16:17]
	v_lshl_add_u64 v[2:3], s[8:9], 0, v[2:3]
	v_lshl_add_u64 v[2:3], s[22:23], 2, v[2:3]
	s_lshl_b32 s72, s13, 2
	v_lshl_add_u64 v[2:3], v[2:3], 0, s[72:73]
	s_waitcnt lgkmcnt(0)
	v_add_f32_e32 v0, v0, v1
	global_store_dword v[2:3], v0, off
